# as v19 plus EpiLru XC row loads hoisted to the epilogue start
# speedup vs baseline: 1.0087x; 1.0027x over previous
; __device__ __forceinline__ float bf_lo(unsigned w) { return __uint_as_float(w << 16); }
; __device__ __forceinline__ float bf_hi(unsigned w) { return __uint_as_float(w & 0xffff0000u); }
; __device__ __forceinline__ float sigmoidf_(float x) { return __builtin_amdgcn_rcpf(1.0f + __builtin_amdgcn_exp2f(-x * LOG2E)); }
;     __device__ __forceinline__ void operator()(const f32x4 (&acc)[2][2][4][2], const Unit& u, int wr, int wc, int fr, int fq, const float (&rs)[2][4]) const {
;     ...
;             sp[j] = 8.0f * LOG2E * (e < 0.02f ? e * (1.0f - e * (0.5f - e * (0.33333333f - 0.25f * e))) : __logf(1.0f + e)); }
; #pragma unroll
;         for (int ai = 0; ai < 2; ++ai)
; #pragma unroll
;             for (int m = 0; m < 4; ++m) { const int row = row0 + ai * HALF + m * 16;
;                 const u32x4 xw = *(const u32x4*)(XC + (size_t)row * 512 + cbase);
;                 float xc[8] = {bf_lo(xw.x), bf_hi(xw.x), bf_lo(xw.y), bf_hi(xw.y), bf_lo(xw.z), bf_hi(xw.z), bf_lo(xw.w), bf_hi(xw.w)};
;                 float la[8], uu[8];
; #pragma unroll
;                 for (int j = 0; j < 8; ++j) { const float r = sigmoidf_(acc[ai][0][m][j >> 2][j & 3] + ba[j]), ig = sigmoidf_(acc[ai][1][m][j >> 2][j & 3] + bx[j]);
;                     la[j] = -r * sp[j]; const float a2 = __builtin_amdgcn_exp2f(2.0f * la[j]); uu[j] = __builtin_sqrtf(fmaxf(1.0f - a2, 0.0f)) * ig * xc[j]; }
.LBB0_1087:
	s_andn2_saveexec_b64 s[2:3], s[68:69]
	v_fmamk_f32 v130, v145, 0xbe800000, v252
	v_fma_f32 v130, -v145, v130, 0.5
	v_fma_f32 v130, -v145, v130, 1.0
	v_mul_f32_e32 v144, v145, v130
	s_or_b64 exec, exec, s[2:3]
	s_lshl_b32 s0, s66, 8
	s_add_i32 s0, s0, s75
	v_mul_f32_e32 v148, 0x4138aa3b, v144
	v_add_u32_e32 v144, s0, v143
	v_ashrrev_i32_e32 v145, 31, v144
	v_ashrrev_i32_e32 v143, 31, v142
	v_lshlrev_b64 v[130:131], 10, v[144:145]
	v_lshl_add_u64 v[130:131], s[4:5], 0, v[130:131]
	v_lshlrev_b64 v[142:143], 1, v[142:143]
	v_lshl_add_u64 v[130:131], v[130:131], 0, v[142:143]
	global_load_dwordx4 v[176:179], v[130:131], off
	v_add_u32_e32 v236, 16, v144
	v_ashrrev_i32_e32 v237, 31, v236
	v_lshlrev_b64 v[236:237], 10, v[236:237]
	v_lshl_add_u64 v[236:237], s[4:5], 0, v[236:237]
	v_lshl_add_u64 v[236:237], v[236:237], 0, v[142:143]
	global_load_dwordx4 v[208:211], v[236:237], off
	v_add_u32_e32 v238, 32, v144
	v_ashrrev_i32_e32 v239, 31, v238
	v_lshlrev_b64 v[238:239], 10, v[238:239]
	v_lshl_add_u64 v[238:239], s[4:5], 0, v[238:239]
	v_lshl_add_u64 v[238:239], v[238:239], 0, v[142:143]
	global_load_dwordx4 v[212:215], v[238:239], off
	v_add_u32_e32 v236, 48, v144
	v_ashrrev_i32_e32 v237, 31, v236
	v_lshlrev_b64 v[236:237], 10, v[236:237]
	v_lshl_add_u64 v[236:237], s[4:5], 0, v[236:237]
	v_lshl_add_u64 v[236:237], v[236:237], 0, v[142:143]
	global_load_dwordx4 v[216:219], v[236:237], off
	v_add_u32_e32 v238, 0x80, v144
	v_ashrrev_i32_e32 v239, 31, v238
	v_lshlrev_b64 v[238:239], 10, v[238:239]
	v_lshl_add_u64 v[238:239], s[4:5], 0, v[238:239]
	v_lshl_add_u64 v[238:239], v[238:239], 0, v[142:143]
	global_load_dwordx4 v[220:223], v[238:239], off
	v_add_u32_e32 v236, 0x90, v144
	v_ashrrev_i32_e32 v237, 31, v236
	v_lshlrev_b64 v[236:237], 10, v[236:237]
	v_lshl_add_u64 v[236:237], s[4:5], 0, v[236:237]
	v_lshl_add_u64 v[236:237], v[236:237], 0, v[142:143]
	global_load_dwordx4 v[224:227], v[236:237], off
	v_add_u32_e32 v238, 0xa0, v144
	v_ashrrev_i32_e32 v239, 31, v238
	v_lshlrev_b64 v[238:239], 10, v[238:239]
	v_lshl_add_u64 v[238:239], s[4:5], 0, v[238:239]
	v_lshl_add_u64 v[238:239], v[238:239], 0, v[142:143]
	global_load_dwordx4 v[228:231], v[238:239], off
	v_add_u32_e32 v236, 0xb0, v144
	v_ashrrev_i32_e32 v237, 31, v236
	v_lshlrev_b64 v[236:237], 10, v[236:237]
	v_lshl_add_u64 v[236:237], s[4:5], 0, v[236:237]
	v_lshl_add_u64 v[236:237], v[236:237], 0, v[142:143]
	global_load_dwordx4 v[232:235], v[236:237], off
	v_add_f32_e32 v126, v126, v173
	v_add_f32_e32 v122, v122, v170
	v_mul_f32_e32 v126, 0xbfb8aa3b, v126
	v_mul_f32_e32 v122, 0xbfb8aa3b, v122
	v_exp_f32_e32 v126, v126
	v_exp_f32_e32 v122, v122
	v_mul_f32_e32 v183, 0x4138aa3b, v183
	v_add_f32_e32 v127, v127, v168
	v_add_f32_e32 v126, 1.0, v126
	v_add_f32_e32 v122, 1.0, v122
	v_rcp_f32_e32 v134, v122
	v_rcp_f32_e64 v122, -v126
	v_add_f32_e32 v123, v123, v166
	v_mul_f32_e32 v127, 0xbfb8aa3b, v127
	v_mul_f32_e32 v123, 0xbfb8aa3b, v123
	v_mul_f32_e32 v122, v183, v122
	v_add_f32_e32 v126, v122, v122
	v_exp_f32_e32 v126, v126
	v_exp_f32_e32 v127, v127
	v_exp_f32_e32 v123, v123
	v_mul_f32_e32 v182, 0x4138aa3b, v182
	v_sub_f32_e32 v126, 1.0, v126
	v_max_f32_e32 v126, 0, v126
	v_cmp_gt_f32_e32 vcc, s17, v126
	v_mul_f32_e32 v135, 0x4f800000, v126
	v_add_f32_e32 v127, 1.0, v127
	v_cndmask_b32_e32 v126, v126, v135, vcc
	v_sqrt_f32_e32 v135, v126
	v_add_f32_e32 v123, 1.0, v123
	v_add_f32_e32 v128, v128, v164
	v_add_f32_e32 v124, v124, v163
	v_add_u32_e32 v169, -1, v135
	v_fma_f32 v171, -v169, v135, v126
	v_cmp_ge_f32_e64 s[2:3], 0, v171
	v_add_u32_e32 v171, 1, v135
	v_mul_f32_e32 v128, 0xbfb8aa3b, v128
	v_cndmask_b32_e64 v169, v135, v169, s[2:3]
	v_fma_f32 v135, -v171, v135, v126
	v_cmp_lt_f32_e64 s[2:3], 0, v135
	v_mul_f32_e32 v124, 0xbfb8aa3b, v124
	v_exp_f32_e32 v128, v128
	v_cndmask_b32_e64 v135, v169, v171, s[2:3]
	v_mul_f32_e32 v169, 0x37800000, v135
	v_cndmask_b32_e32 v135, v135, v169, vcc
	v_cmp_class_f32_e32 vcc, v126, v174
	v_exp_f32_e32 v124, v124
	v_add_f32_e32 v128, 1.0, v128
	v_cndmask_b32_e32 v126, v135, v126, vcc
	v_mul_f32_e32 v126, v134, v126
	v_add_f32_e32 v124, 1.0, v124
	v_mul_f32_e32 v181, 0x4138aa3b, v181
	v_add_f32_e32 v129, v129, v162
	v_add_f32_e32 v125, v125, v161
	v_mul_f32_e32 v129, 0xbfb8aa3b, v129
	v_mul_f32_e32 v125, 0xbfb8aa3b, v125
	v_exp_f32_e32 v129, v129
	v_exp_f32_e32 v125, v125
	v_mul_f32_e32 v172, 0x4138aa3b, v172
	v_add_f32_e32 v118, v118, v159
	v_add_f32_e32 v129, 1.0, v129
	v_add_f32_e32 v125, 1.0, v125
	v_mul_f32_e32 v118, 0xbfb8aa3b, v118
	v_exp_f32_e32 v118, v118
	v_mul_f32_e32 v165, 0x4138aa3b, v165
	v_add_f32_e32 v114, v114, v158
	v_mul_f32_e32 v114, 0xbfb8aa3b, v114
	v_add_f32_e32 v118, 1.0, v118
	v_rcp_f32_e64 v118, -v118
	v_exp_f32_e32 v114, v114
	v_mul_f32_e32 v160, 0x4138aa3b, v160
	v_add_f32_e32 v115, v115, v156
	v_mul_f32_e32 v118, v165, v118
	v_add_f32_e32 v114, 1.0, v114
	v_rcp_f32_e32 v114, v114
	v_mul_f32_e32 v115, 0xbfb8aa3b, v115
	v_exp_f32_e32 v115, v115
	v_mul_f32_e32 v149, 0x4138aa3b, v184
	s_ashr_i32 s65, s64, 31
	s_lshl_b64 s[64:65], s[64:65], 1
	s_waitcnt vmcnt(0)
; __device__ __forceinline__ float sigmoidf_(float x) { return __builtin_amdgcn_rcpf(1.0f + __builtin_amdgcn_exp2f(-x * LOG2E)); }
;     __device__ __forceinline__ void operator()(const f32x4 (&acc)[2][2][4][2], const Unit& u, int wr, int wc, int fr, int fq, const float (&rs)[2][4]) const {
;     ...
;                 for (int j = 0; j < 8; ++j) { const float r = sigmoidf_(acc[ai][0][m][j >> 2][j & 3] + ba[j]), ig = sigmoidf_(acc[ai][1][m][j >> 2][j & 3] + bx[j]);
;                     la[j] = -r * sp[j]; const float a2 = __builtin_amdgcn_exp2f(2.0f * la[j]); uu[j] = __builtin_sqrtf(fmaxf(1.0f - a2, 0.0f)) * ig * xc[j]; }
	v_lshlrev_b32_e32 v130, 16, v176
	v_mul_f32_e32 v126, v126, v130
	v_rcp_f32_e32 v130, v123
	v_rcp_f32_e64 v123, -v127
	v_and_b32_e32 v131, 0xffff0000, v176
	v_lshlrev_b32_e32 v187, 16, v178
	v_add_f32_e32 v115, 1.0, v115
	v_mul_f32_e32 v123, v182, v123
	v_add_f32_e32 v127, v123, v123
	v_exp_f32_e32 v127, v127
	v_rcp_f32_e32 v115, v115
	v_and_b32_e32 v186, 0xffff0000, v178
	v_lshlrev_b32_e32 v185, 16, v179
	v_sub_f32_e32 v127, 1.0, v127
	v_max_f32_e32 v127, 0, v127
	v_cmp_gt_f32_e32 vcc, s17, v127
	v_mul_f32_e32 v134, 0x4f800000, v127
	v_and_b32_e32 v184, 0xffff0000, v179
	v_cndmask_b32_e32 v127, v127, v134, vcc
	v_sqrt_f32_e32 v134, v127
	v_lshlrev_b32_e32 v189, 16, v177
	v_and_b32_e32 v188, 0xffff0000, v177
	v_add_f32_e32 v110, v110, v173
	v_add_u32_e32 v135, -1, v134
	v_fma_f32 v169, -v135, v134, v127
	v_cmp_ge_f32_e64 s[2:3], 0, v169
	v_add_u32_e32 v169, 1, v134
	v_add_f32_e32 v106, v106, v170
	v_cndmask_b32_e64 v135, v134, v135, s[2:3]
	v_fma_f32 v134, -v169, v134, v127
	v_cmp_lt_f32_e64 s[2:3], 0, v134
	v_mul_f32_e32 v110, 0xbfb8aa3b, v110
	v_mul_f32_e32 v106, 0xbfb8aa3b, v106
	v_cndmask_b32_e64 v134, v135, v169, s[2:3]
	v_mul_f32_e32 v135, 0x37800000, v134
	v_cndmask_b32_e32 v134, v134, v135, vcc
	v_cmp_class_f32_e32 vcc, v127, v174
	v_exp_f32_e32 v110, v110
	v_exp_f32_e32 v106, v106
	v_cndmask_b32_e32 v127, v134, v127, vcc
	v_mul_f32_e32 v127, v130, v127
	v_rcp_f32_e32 v130, v124
	v_rcp_f32_e64 v124, -v128
	v_mul_f32_e32 v127, v127, v131
	v_add_f32_e32 v110, 1.0, v110
	v_add_f32_e32 v106, 1.0, v106
	v_mul_f32_e32 v124, v181, v124
	v_add_f32_e32 v128, v124, v124
	v_exp_f32_e32 v128, v128
	v_add_f32_e32 v111, v111, v168
	v_add_f32_e32 v107, v107, v166
	v_mul_f32_e32 v111, 0xbfb8aa3b, v111
	v_sub_f32_e32 v128, 1.0, v128
	v_max_f32_e32 v128, 0, v128
	v_cmp_gt_f32_e32 vcc, s17, v128
	v_mul_f32_e32 v131, 0x4f800000, v128
	v_mul_f32_e32 v107, 0xbfb8aa3b, v107
	v_cndmask_b32_e32 v128, v128, v131, vcc
	v_sqrt_f32_e32 v131, v128
	v_exp_f32_e32 v111, v111
	v_exp_f32_e32 v107, v107
	v_add_f32_e32 v112, v112, v164
	v_add_u32_e32 v134, -1, v131
	v_fma_f32 v135, -v134, v131, v128
	v_cmp_ge_f32_e64 s[2:3], 0, v135
	v_add_u32_e32 v135, 1, v131
	v_add_f32_e32 v111, 1.0, v111
	v_cndmask_b32_e64 v134, v131, v134, s[2:3]
	v_fma_f32 v131, -v135, v131, v128
	v_cmp_lt_f32_e64 s[2:3], 0, v131
	v_add_f32_e32 v107, 1.0, v107
	v_add_f32_e32 v108, v108, v163
	v_cndmask_b32_e64 v131, v134, v135, s[2:3]
	v_mul_f32_e32 v134, 0x37800000, v131
	v_cndmask_b32_e32 v131, v131, v134, vcc
	v_cmp_class_f32_e32 vcc, v128, v174
	v_mul_f32_e32 v112, 0xbfb8aa3b, v112
	v_mul_f32_e32 v108, 0xbfb8aa3b, v108
	v_cndmask_b32_e32 v128, v131, v128, vcc
	v_mul_f32_e32 v128, v130, v128
	v_rcp_f32_e32 v130, v125
	v_rcp_f32_e64 v125, -v129
	v_mul_f32_e32 v128, v128, v189
	v_exp_f32_e32 v112, v112
	v_exp_f32_e32 v108, v108
	v_mul_f32_e32 v125, v172, v125
	v_add_f32_e32 v129, v125, v125
	v_exp_f32_e32 v129, v129
	v_add_f32_e32 v112, 1.0, v112
	v_add_f32_e32 v108, 1.0, v108
	v_add_f32_e32 v113, v113, v162
	v_sub_f32_e32 v129, 1.0, v129
	v_max_f32_e32 v129, 0, v129
	v_cmp_gt_f32_e32 vcc, s17, v129
	v_mul_f32_e32 v131, 0x4f800000, v129
	v_add_f32_e32 v109, v109, v161
	v_cndmask_b32_e32 v129, v129, v131, vcc
	v_sqrt_f32_e32 v131, v129
	v_mul_f32_e32 v113, 0xbfb8aa3b, v113
	v_mul_f32_e32 v109, 0xbfb8aa3b, v109
	v_exp_f32_e32 v113, v113
	v_add_u32_e32 v134, -1, v131
	v_fma_f32 v135, -v134, v131, v129
	v_cmp_ge_f32_e64 s[2:3], 0, v135
	v_add_u32_e32 v135, 1, v131
	v_exp_f32_e32 v109, v109
	v_cndmask_b32_e64 v134, v131, v134, s[2:3]
	v_fma_f32 v131, -v135, v131, v129
	v_cmp_lt_f32_e64 s[2:3], 0, v131
	v_add_f32_e32 v113, 1.0, v113
	v_add_f32_e32 v109, 1.0, v109
	v_cndmask_b32_e64 v131, v134, v135, s[2:3]
	v_mul_f32_e32 v134, 0x37800000, v131
	v_cndmask_b32_e32 v131, v131, v134, vcc
	v_cmp_class_f32_e32 vcc, v129, v174
	v_add_f32_e32 v102, v102, v159
	v_mul_f32_e32 v102, 0xbfb8aa3b, v102
	v_cndmask_b32_e32 v129, v131, v129, vcc
	v_mul_f32_e32 v129, v130, v129
	v_add_f32_e32 v130, v118, v118
	v_exp_f32_e32 v130, v130
	v_mul_f32_e32 v129, v129, v188
	v_exp_f32_e32 v102, v102
	v_add_f32_e32 v98, v98, v158
	v_sub_f32_e32 v130, 1.0, v130
	v_max_f32_e32 v130, 0, v130
	v_cmp_gt_f32_e32 vcc, s17, v130
	v_mul_f32_e32 v131, 0x4f800000, v130
	v_add_f32_e32 v102, 1.0, v102
	v_cndmask_b32_e32 v130, v130, v131, vcc
	v_sqrt_f32_e32 v131, v130
	v_rcp_f32_e64 v102, -v102
	v_mul_f32_e32 v98, 0xbfb8aa3b, v98
	v_exp_f32_e32 v98, v98
	v_add_u32_e32 v134, -1, v131
	v_fma_f32 v135, -v134, v131, v130
	v_cmp_ge_f32_e64 s[2:3], 0, v135
	v_add_u32_e32 v135, 1, v131
	v_mul_f32_e32 v102, v165, v102
	v_cndmask_b32_e64 v134, v131, v134, s[2:3]
	v_fma_f32 v131, -v135, v131, v130
	v_cmp_lt_f32_e64 s[2:3], 0, v131
	v_add_f32_e32 v98, 1.0, v98
	v_rcp_f32_e32 v98, v98
	v_cndmask_b32_e64 v131, v134, v135, s[2:3]
	v_mul_f32_e32 v134, 0x37800000, v131
	v_cndmask_b32_e32 v131, v131, v134, vcc
	v_cmp_class_f32_e32 vcc, v130, v174
	v_add_f32_e32 v99, v99, v156
	v_mul_f32_e32 v99, 0xbfb8aa3b, v99
	v_cndmask_b32_e32 v130, v131, v130, vcc
	v_mul_f32_e32 v114, v114, v130
	v_mul_f32_e32 v130, v114, v187
	v_add_f32_e32 v114, v119, v157
	v_mul_f32_e32 v114, 0xbfb8aa3b, v114
	v_exp_f32_e32 v114, v114
	v_exp_f32_e32 v99, v99
	v_add_f32_e32 v94, v94, v173
	v_add_f32_e32 v90, v90, v170
	v_add_f32_e32 v114, 1.0, v114
	v_rcp_f32_e64 v114, -v114
	v_add_f32_e32 v99, 1.0, v99
	v_rcp_f32_e32 v99, v99
	v_mul_f32_e32 v94, 0xbfb8aa3b, v94
	v_mul_f32_e32 v119, v160, v114
	v_add_f32_e32 v114, v119, v119
	v_exp_f32_e32 v114, v114
	v_mul_f32_e32 v90, 0xbfb8aa3b, v90
	v_exp_f32_e32 v94, v94
	v_exp_f32_e32 v90, v90
	v_sub_f32_e32 v114, 1.0, v114
; __device__ __forceinline__ unsigned cvt_pk_bf16(float lo, float hi) { unsigned r; asm volatile("v_cvt_pk_bf16_f32 %0, %1, %2" : "=v"(r) : "v"(lo), "v"(hi)); return r; }
; __device__ __forceinline__ float sigmoidf_(float x) { return __builtin_amdgcn_rcpf(1.0f + __builtin_amdgcn_exp2f(-x * LOG2E)); }
;     __device__ __forceinline__ void operator()(const f32x4 (&acc)[2][2][4][2], const Unit& u, int wr, int wc, int fr, int fq, const float (&rs)[2][4]) const {
;     ...
;                 for (int j = 0; j < 8; ++j) { const float r = sigmoidf_(acc[ai][0][m][j >> 2][j & 3] + ba[j]), ig = sigmoidf_(acc[ai][1][m][j >> 2][j & 3] + bx[j]);
;                     la[j] = -r * sp[j]; const float a2 = __builtin_amdgcn_exp2f(2.0f * la[j]); uu[j] = __builtin_sqrtf(fmaxf(1.0f - a2, 0.0f)) * ig * xc[j]; }
;                 u32x4 w; w.x = cvt_pk_bf16(la[0], la[1]); w.y = cvt_pk_bf16(la[2], la[3]); w.z = cvt_pk_bf16(la[4], la[5]); w.w = cvt_pk_bf16(la[6], la[7]);
;                 *(u32x4*)(LA + (size_t)row * 1024 + dir * 512 + cbase) = w;
;                 w.x = cvt_pk_bf16(uu[0], uu[1]); w.y = cvt_pk_bf16(uu[2], uu[3]); w.z = cvt_pk_bf16(uu[4], uu[5]); w.w = cvt_pk_bf16(uu[6], uu[7]);
;                 *(u32x4*)(U + (size_t)row * 1024 + dir * 512 + cbase) = w; }
	v_max_f32_e32 v114, 0, v114
	v_cmp_gt_f32_e32 vcc, s17, v114
	v_mul_f32_e32 v131, 0x4f800000, v114
	v_add_f32_e32 v94, 1.0, v94
	v_cndmask_b32_e32 v114, v114, v131, vcc
	v_sqrt_f32_e32 v131, v114
	v_add_f32_e32 v90, 1.0, v90
	v_add_f32_e32 v95, v95, v168
	v_add_f32_e32 v91, v91, v166
	v_add_u32_e32 v134, -1, v131
	v_fma_f32 v135, -v134, v131, v114
	v_cmp_ge_f32_e64 s[2:3], 0, v135
	v_add_u32_e32 v135, 1, v131
	v_mul_f32_e32 v95, 0xbfb8aa3b, v95
	v_cndmask_b32_e64 v134, v131, v134, s[2:3]
	v_fma_f32 v131, -v135, v131, v114
	v_cmp_lt_f32_e64 s[2:3], 0, v131
	v_mul_f32_e32 v91, 0xbfb8aa3b, v91
	v_exp_f32_e32 v95, v95
	v_cndmask_b32_e64 v131, v134, v135, s[2:3]
	v_mul_f32_e32 v134, 0x37800000, v131
	v_cndmask_b32_e32 v131, v131, v134, vcc
	v_cmp_class_f32_e32 vcc, v114, v174
	v_exp_f32_e32 v91, v91
	v_add_f32_e32 v95, 1.0, v95
	v_cndmask_b32_e32 v114, v131, v114, vcc
	v_mul_f32_e32 v114, v115, v114
	v_mul_f32_e32 v131, v114, v186
	v_add_f32_e32 v114, v120, v155
	v_mul_f32_e32 v114, 0xbfb8aa3b, v114
	v_exp_f32_e32 v114, v114
	v_add_f32_e32 v115, v116, v154
	v_mul_f32_e32 v115, 0xbfb8aa3b, v115
	v_exp_f32_e32 v115, v115
	v_add_f32_e32 v114, 1.0, v114
	v_rcp_f32_e64 v114, -v114
	v_add_f32_e32 v91, 1.0, v91
	v_add_f32_e32 v115, 1.0, v115
	v_rcp_f32_e32 v115, v115
	v_mul_f32_e32 v120, v149, v114
	v_add_f32_e32 v114, v120, v120
	v_exp_f32_e32 v114, v114
	v_add_f32_e32 v96, v96, v164
	v_add_f32_e32 v92, v92, v163
	v_mul_f32_e32 v96, 0xbfb8aa3b, v96
	v_sub_f32_e32 v114, 1.0, v114
	v_max_f32_e32 v114, 0, v114
	v_cmp_gt_f32_e32 vcc, s17, v114
	v_mul_f32_e32 v116, 0x4f800000, v114
	v_mul_f32_e32 v92, 0xbfb8aa3b, v92
	v_cndmask_b32_e32 v114, v114, v116, vcc
	v_sqrt_f32_e32 v116, v114
	v_exp_f32_e32 v96, v96
	v_exp_f32_e32 v92, v92
	v_add_f32_e32 v97, v97, v162
	v_add_u32_e32 v134, -1, v116
	v_fma_f32 v135, -v134, v116, v114
	v_cmp_ge_f32_e64 s[2:3], 0, v135
	v_add_u32_e32 v135, 1, v116
	v_add_f32_e32 v96, 1.0, v96
	v_cndmask_b32_e64 v134, v116, v134, s[2:3]
	v_fma_f32 v116, -v135, v116, v114
	v_cmp_lt_f32_e64 s[2:3], 0, v116
	v_add_f32_e32 v92, 1.0, v92
	v_add_f32_e32 v93, v93, v161
	v_cndmask_b32_e64 v116, v134, v135, s[2:3]
	v_mul_f32_e32 v134, 0x37800000, v116
	v_cndmask_b32_e32 v116, v116, v134, vcc
	v_cmp_class_f32_e32 vcc, v114, v174
	v_mul_f32_e32 v97, 0xbfb8aa3b, v97
	v_mul_f32_e32 v93, 0xbfb8aa3b, v93
	v_cndmask_b32_e32 v114, v116, v114, vcc
	v_mul_f32_e32 v114, v115, v114
	v_mul_f32_e32 v134, v114, v185
	v_add_f32_e32 v114, v121, v147
	v_mul_f32_e32 v114, 0xbfb8aa3b, v114
	v_exp_f32_e32 v114, v114
	v_add_f32_e32 v115, v117, v146
	v_mul_f32_e32 v115, 0xbfb8aa3b, v115
	v_exp_f32_e32 v115, v115
	v_add_f32_e32 v114, 1.0, v114
	v_rcp_f32_e64 v114, -v114
	v_exp_f32_e32 v97, v97
	v_add_f32_e32 v115, 1.0, v115
	v_rcp_f32_e32 v115, v115
	v_mul_f32_e32 v117, v148, v114
	v_add_f32_e32 v114, v117, v117
	v_exp_f32_e32 v114, v114
	v_exp_f32_e32 v93, v93
	v_add_f32_e32 v97, 1.0, v97
	v_add_f32_e32 v86, v86, v159
	v_sub_f32_e32 v114, 1.0, v114
	v_max_f32_e32 v114, 0, v114
	v_cmp_gt_f32_e32 vcc, s17, v114
	v_mul_f32_e32 v116, 0x4f800000, v114
	v_add_f32_e32 v93, 1.0, v93
	v_cndmask_b32_e32 v114, v114, v116, vcc
	v_sqrt_f32_e32 v116, v114
	v_mul_f32_e32 v86, 0xbfb8aa3b, v86
	v_exp_f32_e32 v86, v86
	v_add_f32_e32 v82, v82, v158
	v_add_u32_e32 v121, -1, v116
	v_fma_f32 v135, -v121, v116, v114
	v_cmp_ge_f32_e64 s[2:3], 0, v135
	v_add_u32_e32 v135, 1, v116
	v_add_f32_e32 v86, 1.0, v86
	v_cndmask_b32_e64 v121, v116, v121, s[2:3]
	v_fma_f32 v116, -v135, v116, v114
	v_cmp_lt_f32_e64 s[2:3], 0, v116
	v_rcp_f32_e64 v86, -v86
	v_mul_f32_e32 v82, 0xbfb8aa3b, v82
	v_cndmask_b32_e64 v116, v121, v135, s[2:3]
	v_mul_f32_e32 v121, 0x37800000, v116
	v_cndmask_b32_e32 v116, v116, v121, vcc
	v_cmp_class_f32_e32 vcc, v114, v174
	v_mul_f32_e32 v86, v165, v86
	v_exp_f32_e32 v82, v82
	v_cndmask_b32_e32 v114, v116, v114, vcc
	v_mul_f32_e32 v114, v115, v114
	v_mul_f32_e32 v135, v114, v184
	v_cvt_pk_bf16_f32 v114, v122, v123
	v_cvt_pk_bf16_f32 v115, v124, v125
	v_cvt_pk_bf16_f32 v116, v118, v119
	v_lshlrev_b64 v[118:119], 11, v[144:145]
	v_cvt_pk_bf16_f32 v117, v120, v117
	v_lshl_add_u64 v[120:121], s[76:77], 0, v[118:119]
	v_lshl_add_u64 v[120:121], v[120:121], 0, s[64:65]
	v_lshl_add_u64 v[118:119], s[56:57], 0, v[118:119]
	v_lshl_add_u64 v[120:121], v[120:121], 0, v[142:143]
	v_lshl_add_u64 v[118:119], v[118:119], 0, s[64:65]
	global_store_dwordx4 v[120:121], v[114:117], off
	v_lshl_add_u64 v[118:119], v[118:119], 0, v[142:143]
	v_add_f32_e32 v82, 1.0, v82
	v_cvt_pk_bf16_f32 v114, v126, v127
	v_cvt_pk_bf16_f32 v115, v128, v129
	v_cvt_pk_bf16_f32 v116, v130, v131
	v_cvt_pk_bf16_f32 v117, v134, v135
	global_store_dwordx4 v[118:119], v[114:117], off
	v_rcp_f32_e32 v82, v82
	v_add_f32_e32 v83, v83, v156
	v_add_u32_e32 v114, 16, v144
	v_ashrrev_i32_e32 v115, 31, v114
	v_lshlrev_b64 v[116:117], 10, v[114:115]
	v_lshl_add_u64 v[116:117], s[4:5], 0, v[116:117]
	v_lshl_add_u64 v[116:117], v[116:117], 0, v[142:143]
	s_nop 0
	v_mul_f32_e32 v83, 0xbfb8aa3b, v83
	v_exp_f32_e32 v83, v83
	v_add_f32_e32 v76, v76, v173
	v_add_f32_e32 v72, v72, v170
	v_mul_f32_e32 v76, 0xbfb8aa3b, v76
	v_add_f32_e32 v83, 1.0, v83
	v_rcp_f32_e32 v83, v83
	v_mul_f32_e32 v72, 0xbfb8aa3b, v72
	v_exp_f32_e32 v76, v76
	v_exp_f32_e32 v72, v72
	v_add_f32_e32 v77, v77, v168
	v_add_f32_e32 v73, v73, v166
	v_add_f32_e32 v76, 1.0, v76
	v_add_f32_e32 v72, 1.0, v72
	v_mul_f32_e32 v77, 0xbfb8aa3b, v77
	v_mul_f32_e32 v73, 0xbfb8aa3b, v73
	v_exp_f32_e32 v77, v77
	v_exp_f32_e32 v73, v73
	v_add_f32_e32 v78, v78, v164
	v_add_f32_e32 v74, v74, v163
	v_add_f32_e32 v77, 1.0, v77
	v_add_f32_e32 v73, 1.0, v73
	v_mul_f32_e32 v78, 0xbfb8aa3b, v78
; __device__ __forceinline__ float bf_lo(unsigned w) { return __uint_as_float(w << 16); }
; __device__ __forceinline__ float bf_hi(unsigned w) { return __uint_as_float(w & 0xffff0000u); }
; __device__ __forceinline__ float sigmoidf_(float x) { return __builtin_amdgcn_rcpf(1.0f + __builtin_amdgcn_exp2f(-x * LOG2E)); }
;     __device__ __forceinline__ void operator()(const f32x4 (&acc)[2][2][4][2], const Unit& u, int wr, int wc, int fr, int fq, const float (&rs)[2][4]) const {
;     ...
;             for (int m = 0; m < 4; ++m) { const int row = row0 + ai * HALF + m * 16;
;                 const u32x4 xw = *(const u32x4*)(XC + (size_t)row * 512 + cbase);
;                 float xc[8] = {bf_lo(xw.x), bf_hi(xw.x), bf_lo(xw.y), bf_hi(xw.y), bf_lo(xw.z), bf_hi(xw.z), bf_lo(xw.w), bf_hi(xw.w)};
;                 float la[8], uu[8];
; #pragma unroll
;                 for (int j = 0; j < 8; ++j) { const float r = sigmoidf_(acc[ai][0][m][j >> 2][j & 3] + ba[j]), ig = sigmoidf_(acc[ai][1][m][j >> 2][j & 3] + bx[j]);
;                     la[j] = -r * sp[j]; const float a2 = __builtin_amdgcn_exp2f(2.0f * la[j]); uu[j] = __builtin_sqrtf(fmaxf(1.0f - a2, 0.0f)) * ig * xc[j]; }
	v_mul_f32_e32 v74, 0xbfb8aa3b, v74
	v_exp_f32_e32 v78, v78
	v_exp_f32_e32 v74, v74
	v_add_f32_e32 v79, v79, v162
	v_add_f32_e32 v75, v75, v161
	v_add_f32_e32 v78, 1.0, v78
	v_add_f32_e32 v74, 1.0, v74
	v_mul_f32_e32 v79, 0xbfb8aa3b, v79
	v_mul_f32_e32 v75, 0xbfb8aa3b, v75
	v_exp_f32_e32 v79, v79
	v_exp_f32_e32 v75, v75
	v_add_f32_e32 v68, v68, v159
	v_mul_f32_e32 v68, 0xbfb8aa3b, v68
	v_add_f32_e32 v79, 1.0, v79
	v_add_f32_e32 v75, 1.0, v75
	v_exp_f32_e32 v68, v68
	v_add_f32_e32 v64, v64, v158
	v_mul_f32_e32 v64, 0xbfb8aa3b, v64
	v_exp_f32_e32 v64, v64
	v_add_f32_e32 v68, 1.0, v68
	v_rcp_f32_e64 v68, -v68
	v_add_f32_e32 v65, v65, v156
	v_add_f32_e32 v64, 1.0, v64
	v_rcp_f32_e32 v64, v64
	v_mul_f32_e32 v68, v165, v68
	v_mul_f32_e32 v65, 0xbfb8aa3b, v65
	v_exp_f32_e32 v65, v65
	v_add_f32_e32 v60, v60, v173
	v_add_f32_e32 v56, v56, v170
	v_mul_f32_e32 v60, 0xbfb8aa3b, v60
	v_add_f32_e32 v65, 1.0, v65
	v_rcp_f32_e32 v65, v65
	v_mul_f32_e32 v56, 0xbfb8aa3b, v56
	v_exp_f32_e32 v60, v60
	v_exp_f32_e32 v56, v56
	v_add_f32_e32 v61, v61, v168
	v_add_f32_e32 v57, v57, v166
	v_add_f32_e32 v60, 1.0, v60
	v_add_f32_e32 v56, 1.0, v56
	v_mul_f32_e32 v61, 0xbfb8aa3b, v61
	v_mul_f32_e32 v57, 0xbfb8aa3b, v57
	v_exp_f32_e32 v61, v61
	v_exp_f32_e32 v57, v57
	v_add_f32_e32 v62, v62, v164
	v_add_f32_e32 v58, v58, v163
	v_add_f32_e32 v61, 1.0, v61
	v_add_f32_e32 v57, 1.0, v57
	v_mul_f32_e32 v62, 0xbfb8aa3b, v62
	v_mul_f32_e32 v58, 0xbfb8aa3b, v58
	v_exp_f32_e32 v62, v62
	v_exp_f32_e32 v58, v58
	v_add_f32_e32 v63, v63, v162
	v_add_f32_e32 v59, v59, v161
	v_add_f32_e32 v62, 1.0, v62
	v_add_f32_e32 v58, 1.0, v58
	v_mul_f32_e32 v63, 0xbfb8aa3b, v63
	v_lshlrev_b32_e32 v124, 16, v208
	v_and_b32_e32 v125, 0xffff0000, v208
	v_lshlrev_b32_e32 v126, 16, v209
	v_and_b32_e32 v120, 0xffff0000, v209
	v_rcp_f32_e32 v121, v106
	v_rcp_f32_e64 v106, -v110
	v_lshlrev_b32_e32 v119, 16, v210
	v_and_b32_e32 v118, 0xffff0000, v210
	v_lshlrev_b32_e32 v117, 16, v211
	v_mul_f32_e32 v106, v183, v106
	v_add_f32_e32 v110, v106, v106
	v_exp_f32_e32 v110, v110
	v_and_b32_e32 v116, 0xffff0000, v211
	v_mul_f32_e32 v59, 0xbfb8aa3b, v59
	v_exp_f32_e32 v63, v63
	v_sub_f32_e32 v110, 1.0, v110
	v_max_f32_e32 v110, 0, v110
	v_cmp_gt_f32_e32 vcc, s17, v110
	v_mul_f32_e32 v122, 0x4f800000, v110
	v_exp_f32_e32 v59, v59
	v_cndmask_b32_e32 v110, v110, v122, vcc
	v_sqrt_f32_e32 v122, v110
	v_add_f32_e32 v63, 1.0, v63
	v_add_f32_e32 v59, 1.0, v59
	v_add_f32_e32 v52, v52, v159
	v_add_u32_e32 v123, -1, v122
	v_fma_f32 v127, -v123, v122, v110
	v_cmp_ge_f32_e64 s[2:3], 0, v127
	v_add_u32_e32 v127, 1, v122
	v_mul_f32_e32 v52, 0xbfb8aa3b, v52
	v_cndmask_b32_e64 v123, v122, v123, s[2:3]
	v_fma_f32 v122, -v127, v122, v110
	v_cmp_lt_f32_e64 s[2:3], 0, v122
	v_exp_f32_e32 v52, v52
	v_add_f32_e32 v48, v48, v158
	v_cndmask_b32_e64 v122, v123, v127, s[2:3]
	v_mul_f32_e32 v123, 0x37800000, v122
	v_cndmask_b32_e32 v122, v122, v123, vcc
	v_cmp_class_f32_e32 vcc, v110, v174
	v_add_f32_e32 v52, 1.0, v52
	v_rcp_f32_e64 v52, -v52
	v_cndmask_b32_e32 v110, v122, v110, vcc
	v_mul_f32_e32 v110, v121, v110
	v_rcp_f32_e32 v121, v107
	v_rcp_f32_e64 v107, -v111
	v_mul_f32_e32 v110, v110, v124
	v_mul_f32_e32 v52, v165, v52
	v_mul_f32_e32 v48, 0xbfb8aa3b, v48
	v_mul_f32_e32 v107, v182, v107
	v_add_f32_e32 v111, v107, v107
	v_exp_f32_e32 v111, v111
	v_exp_f32_e32 v48, v48
	v_add_f32_e32 v49, v49, v156
	v_mul_f32_e32 v49, 0xbfb8aa3b, v49
	v_sub_f32_e32 v111, 1.0, v111
	v_max_f32_e32 v111, 0, v111
	v_cmp_gt_f32_e32 vcc, s17, v111
	v_mul_f32_e32 v122, 0x4f800000, v111
	v_add_f32_e32 v48, 1.0, v48
	v_cndmask_b32_e32 v111, v111, v122, vcc
	v_sqrt_f32_e32 v122, v111
	v_rcp_f32_e32 v48, v48
	v_exp_f32_e32 v49, v49
	v_add_f32_e32 v44, v44, v173
	v_add_u32_e32 v123, -1, v122
	v_fma_f32 v124, -v123, v122, v111
	v_cmp_ge_f32_e64 s[2:3], 0, v124
	v_add_u32_e32 v124, 1, v122
	v_add_f32_e32 v49, 1.0, v49
	v_cndmask_b32_e64 v123, v122, v123, s[2:3]
	v_fma_f32 v122, -v124, v122, v111
	v_cmp_lt_f32_e64 s[2:3], 0, v122
	v_rcp_f32_e32 v49, v49
	v_add_f32_e32 v40, v40, v170
	v_cndmask_b32_e64 v122, v123, v124, s[2:3]
	v_mul_f32_e32 v123, 0x37800000, v122
	v_cndmask_b32_e32 v122, v122, v123, vcc
	v_cmp_class_f32_e32 vcc, v111, v174
	v_mul_f32_e32 v44, 0xbfb8aa3b, v44
	v_mul_f32_e32 v40, 0xbfb8aa3b, v40
	v_cndmask_b32_e32 v111, v122, v111, vcc
	v_mul_f32_e32 v111, v121, v111
	v_rcp_f32_e32 v121, v108
	v_rcp_f32_e64 v108, -v112
	v_mul_f32_e32 v111, v111, v125
	v_exp_f32_e32 v44, v44
	v_exp_f32_e32 v40, v40
	v_mul_f32_e32 v108, v181, v108
	v_add_f32_e32 v112, v108, v108
	v_exp_f32_e32 v112, v112
	v_add_f32_e32 v44, 1.0, v44
	v_add_f32_e32 v40, 1.0, v40
	v_add_f32_e32 v45, v45, v168
	v_sub_f32_e32 v112, 1.0, v112
	v_max_f32_e32 v112, 0, v112
	v_cmp_gt_f32_e32 vcc, s17, v112
	v_mul_f32_e32 v122, 0x4f800000, v112
	v_add_f32_e32 v41, v41, v166
	v_cndmask_b32_e32 v112, v112, v122, vcc
	v_sqrt_f32_e32 v122, v112
	v_mul_f32_e32 v45, 0xbfb8aa3b, v45
	v_mul_f32_e32 v41, 0xbfb8aa3b, v41
	v_exp_f32_e32 v45, v45
	v_add_u32_e32 v123, -1, v122
	v_fma_f32 v124, -v123, v122, v112
	v_cmp_ge_f32_e64 s[2:3], 0, v124
	v_add_u32_e32 v124, 1, v122
	v_exp_f32_e32 v41, v41
	v_cndmask_b32_e64 v123, v122, v123, s[2:3]
	v_fma_f32 v122, -v124, v122, v112
	v_cmp_lt_f32_e64 s[2:3], 0, v122
	v_add_f32_e32 v45, 1.0, v45
	v_add_f32_e32 v41, 1.0, v41
	v_cndmask_b32_e64 v122, v123, v124, s[2:3]
	v_mul_f32_e32 v123, 0x37800000, v122
	v_cndmask_b32_e32 v122, v122, v123, vcc
	v_cmp_class_f32_e32 vcc, v112, v174
	v_add_f32_e32 v46, v46, v164
	v_add_f32_e32 v42, v42, v163
	v_cndmask_b32_e32 v112, v122, v112, vcc
	v_mul_f32_e32 v112, v121, v112
	v_rcp_f32_e32 v121, v109
	v_rcp_f32_e64 v109, -v113
; __device__ __forceinline__ float sigmoidf_(float x) { return __builtin_amdgcn_rcpf(1.0f + __builtin_amdgcn_exp2f(-x * LOG2E)); }
;     __device__ __forceinline__ void operator()(const f32x4 (&acc)[2][2][4][2], const Unit& u, int wr, int wc, int fr, int fq, const float (&rs)[2][4]) const {
;     ...
;                 for (int j = 0; j < 8; ++j) { const float r = sigmoidf_(acc[ai][0][m][j >> 2][j & 3] + ba[j]), ig = sigmoidf_(acc[ai][1][m][j >> 2][j & 3] + bx[j]);
;                     la[j] = -r * sp[j]; const float a2 = __builtin_amdgcn_exp2f(2.0f * la[j]); uu[j] = __builtin_sqrtf(fmaxf(1.0f - a2, 0.0f)) * ig * xc[j]; }
	v_mul_f32_e32 v112, v112, v126
	v_mul_f32_e32 v46, 0xbfb8aa3b, v46
	v_mul_f32_e32 v42, 0xbfb8aa3b, v42
	v_mul_f32_e32 v109, v172, v109
	v_add_f32_e32 v113, v109, v109
	v_exp_f32_e32 v113, v113
	v_exp_f32_e32 v46, v46
	v_exp_f32_e32 v42, v42
	v_add_f32_e32 v47, v47, v162
	v_sub_f32_e32 v113, 1.0, v113
	v_max_f32_e32 v113, 0, v113
	v_cmp_gt_f32_e32 vcc, s17, v113
	v_mul_f32_e32 v122, 0x4f800000, v113
	v_add_f32_e32 v46, 1.0, v46
	v_cndmask_b32_e32 v113, v113, v122, vcc
	v_sqrt_f32_e32 v122, v113
	v_add_f32_e32 v42, 1.0, v42
	v_add_f32_e32 v43, v43, v161
	v_mul_f32_e32 v47, 0xbfb8aa3b, v47
	v_add_u32_e32 v123, -1, v122
	v_fma_f32 v124, -v123, v122, v113
	v_cmp_ge_f32_e64 s[2:3], 0, v124
	v_add_u32_e32 v124, 1, v122
	v_mul_f32_e32 v43, 0xbfb8aa3b, v43
	v_cndmask_b32_e64 v123, v122, v123, s[2:3]
	v_fma_f32 v122, -v124, v122, v113
	v_cmp_lt_f32_e64 s[2:3], 0, v122
	v_exp_f32_e32 v47, v47
	v_exp_f32_e32 v43, v43
	v_cndmask_b32_e64 v122, v123, v124, s[2:3]
	v_mul_f32_e32 v123, 0x37800000, v122
	v_cndmask_b32_e32 v122, v122, v123, vcc
	v_cmp_class_f32_e32 vcc, v113, v174
	v_add_f32_e32 v47, 1.0, v47
	v_add_f32_e32 v43, 1.0, v43
	v_cndmask_b32_e32 v113, v122, v113, vcc
	v_mul_f32_e32 v113, v121, v113
	v_mul_f32_e32 v113, v113, v120
	v_add_f32_e32 v120, v102, v102
	v_exp_f32_e32 v120, v120
	v_add_f32_e32 v36, v36, v159
	v_mul_f32_e32 v36, 0xbfb8aa3b, v36
	v_exp_f32_e32 v36, v36
	v_sub_f32_e32 v120, 1.0, v120
	v_max_f32_e32 v120, 0, v120
	v_cmp_gt_f32_e32 vcc, s17, v120
	v_mul_f32_e32 v121, 0x4f800000, v120
	v_add_f32_e32 v36, 1.0, v36
	v_cndmask_b32_e32 v120, v120, v121, vcc
	v_sqrt_f32_e32 v121, v120
	v_rcp_f32_e64 v36, -v36
	v_add_f32_e32 v32, v32, v158
	v_mul_f32_e32 v32, 0xbfb8aa3b, v32
	v_add_u32_e32 v122, -1, v121
	v_fma_f32 v123, -v122, v121, v120
	v_cmp_ge_f32_e64 s[2:3], 0, v123
	v_add_u32_e32 v123, 1, v121
	v_mul_f32_e32 v36, v165, v36
	v_cndmask_b32_e64 v122, v121, v122, s[2:3]
	v_fma_f32 v121, -v123, v121, v120
	v_cmp_lt_f32_e64 s[2:3], 0, v121
	v_exp_f32_e32 v32, v32
	v_add_f32_e32 v33, v33, v156
	v_cndmask_b32_e64 v121, v122, v123, s[2:3]
	v_mul_f32_e32 v122, 0x37800000, v121
	v_cndmask_b32_e32 v121, v121, v122, vcc
	v_cmp_class_f32_e32 vcc, v120, v174
	v_add_f32_e32 v32, 1.0, v32
	v_rcp_f32_e32 v32, v32
	v_cndmask_b32_e32 v120, v121, v120, vcc
	v_mul_f32_e32 v98, v98, v120
	v_mul_f32_e32 v119, v98, v119
	v_add_f32_e32 v98, v103, v157
	v_mul_f32_e32 v98, 0xbfb8aa3b, v98
	v_exp_f32_e32 v98, v98
	v_mul_f32_e32 v33, 0xbfb8aa3b, v33
	v_exp_f32_e32 v33, v33
	v_add_f32_e32 v28, v28, v173
	v_add_f32_e32 v98, 1.0, v98
	v_rcp_f32_e64 v98, -v98
	v_add_f32_e32 v33, 1.0, v33
	v_rcp_f32_e32 v33, v33
	v_add_f32_e32 v24, v24, v170
	v_mul_f32_e32 v103, v160, v98
	v_add_f32_e32 v98, v103, v103
	v_exp_f32_e32 v98, v98
	v_mul_f32_e32 v28, 0xbfb8aa3b, v28
	v_mul_f32_e32 v24, 0xbfb8aa3b, v24
	v_exp_f32_e32 v28, v28
	v_sub_f32_e32 v98, 1.0, v98
	v_max_f32_e32 v98, 0, v98
	v_cmp_gt_f32_e32 vcc, s17, v98
	v_mul_f32_e32 v120, 0x4f800000, v98
	v_exp_f32_e32 v24, v24
	v_cndmask_b32_e32 v98, v98, v120, vcc
	v_sqrt_f32_e32 v120, v98
	v_add_f32_e32 v28, 1.0, v28
	v_add_f32_e32 v24, 1.0, v24
	v_add_f32_e32 v29, v29, v168
	v_add_u32_e32 v121, -1, v120
	v_fma_f32 v122, -v121, v120, v98
	v_cmp_ge_f32_e64 s[2:3], 0, v122
	v_add_u32_e32 v122, 1, v120
	v_add_f32_e32 v25, v25, v166
	v_cndmask_b32_e64 v121, v120, v121, s[2:3]
	v_fma_f32 v120, -v122, v120, v98
	v_cmp_lt_f32_e64 s[2:3], 0, v120
	v_mul_f32_e32 v29, 0xbfb8aa3b, v29
	v_mul_f32_e32 v25, 0xbfb8aa3b, v25
	v_cndmask_b32_e64 v120, v121, v122, s[2:3]
	v_mul_f32_e32 v121, 0x37800000, v120
	v_cndmask_b32_e32 v120, v120, v121, vcc
	v_cmp_class_f32_e32 vcc, v98, v174
	v_exp_f32_e32 v29, v29
	v_exp_f32_e32 v25, v25
	v_cndmask_b32_e32 v98, v120, v98, vcc
	v_mul_f32_e32 v98, v99, v98
	v_mul_f32_e32 v118, v98, v118
	v_add_f32_e32 v98, v104, v155
	v_mul_f32_e32 v98, 0xbfb8aa3b, v98
	v_exp_f32_e32 v98, v98
	v_add_f32_e32 v99, v100, v154
	v_mul_f32_e32 v99, 0xbfb8aa3b, v99
	v_exp_f32_e32 v99, v99
	v_add_f32_e32 v98, 1.0, v98
	v_rcp_f32_e64 v98, -v98
	v_add_f32_e32 v29, 1.0, v29
	v_add_f32_e32 v99, 1.0, v99
	v_rcp_f32_e32 v99, v99
	v_mul_f32_e32 v104, v149, v98
	v_add_f32_e32 v98, v104, v104
	v_exp_f32_e32 v98, v98
	v_add_f32_e32 v25, 1.0, v25
	v_add_f32_e32 v30, v30, v164
	v_add_f32_e32 v26, v26, v163
	v_sub_f32_e32 v98, 1.0, v98
	v_max_f32_e32 v98, 0, v98
	v_cmp_gt_f32_e32 vcc, s17, v98
	v_mul_f32_e32 v100, 0x4f800000, v98
	v_mul_f32_e32 v30, 0xbfb8aa3b, v30
	v_cndmask_b32_e32 v98, v98, v100, vcc
	v_sqrt_f32_e32 v100, v98
	v_mul_f32_e32 v26, 0xbfb8aa3b, v26
	v_exp_f32_e32 v30, v30
	v_exp_f32_e32 v26, v26
	v_add_u32_e32 v120, -1, v100
	v_fma_f32 v121, -v120, v100, v98
	v_cmp_ge_f32_e64 s[2:3], 0, v121
	v_add_u32_e32 v121, 1, v100
	v_add_f32_e32 v30, 1.0, v30
	v_cndmask_b32_e64 v120, v100, v120, s[2:3]
	v_fma_f32 v100, -v121, v100, v98
	v_cmp_lt_f32_e64 s[2:3], 0, v100
	v_add_f32_e32 v26, 1.0, v26
	v_add_f32_e32 v31, v31, v162
	v_cndmask_b32_e64 v100, v120, v121, s[2:3]
	v_mul_f32_e32 v120, 0x37800000, v100
	v_cndmask_b32_e32 v100, v100, v120, vcc
	v_cmp_class_f32_e32 vcc, v98, v174
	v_add_f32_e32 v27, v27, v161
	v_mul_f32_e32 v31, 0xbfb8aa3b, v31
	v_cndmask_b32_e32 v98, v100, v98, vcc
	v_mul_f32_e32 v98, v99, v98
	v_mul_f32_e32 v117, v98, v117
	v_add_f32_e32 v98, v105, v147
	v_mul_f32_e32 v98, 0xbfb8aa3b, v98
	v_exp_f32_e32 v98, v98
	v_add_f32_e32 v99, v101, v146
	v_mul_f32_e32 v99, 0xbfb8aa3b, v99
	v_exp_f32_e32 v99, v99
	v_add_f32_e32 v98, 1.0, v98
	v_rcp_f32_e64 v98, -v98
	v_mul_f32_e32 v27, 0xbfb8aa3b, v27
	v_add_f32_e32 v99, 1.0, v99
	v_rcp_f32_e32 v99, v99
	v_mul_f32_e32 v101, v148, v98
	v_add_f32_e32 v98, v101, v101
; __device__ __forceinline__ unsigned cvt_pk_bf16(float lo, float hi) { unsigned r; asm volatile("v_cvt_pk_bf16_f32 %0, %1, %2" : "=v"(r) : "v"(lo), "v"(hi)); return r; }
; __device__ __forceinline__ float sigmoidf_(float x) { return __builtin_amdgcn_rcpf(1.0f + __builtin_amdgcn_exp2f(-x * LOG2E)); }
;     __device__ __forceinline__ void operator()(const f32x4 (&acc)[2][2][4][2], const Unit& u, int wr, int wc, int fr, int fq, const float (&rs)[2][4]) const {
;     ...
;                 for (int j = 0; j < 8; ++j) { const float r = sigmoidf_(acc[ai][0][m][j >> 2][j & 3] + ba[j]), ig = sigmoidf_(acc[ai][1][m][j >> 2][j & 3] + bx[j]);
;                     la[j] = -r * sp[j]; const float a2 = __builtin_amdgcn_exp2f(2.0f * la[j]); uu[j] = __builtin_sqrtf(fmaxf(1.0f - a2, 0.0f)) * ig * xc[j]; }
;                 u32x4 w; w.x = cvt_pk_bf16(la[0], la[1]); w.y = cvt_pk_bf16(la[2], la[3]); w.z = cvt_pk_bf16(la[4], la[5]); w.w = cvt_pk_bf16(la[6], la[7]);
;                 *(u32x4*)(LA + (size_t)row * 1024 + dir * 512 + cbase) = w;
;                 w.x = cvt_pk_bf16(uu[0], uu[1]); w.y = cvt_pk_bf16(uu[2], uu[3]); w.z = cvt_pk_bf16(uu[4], uu[5]); w.w = cvt_pk_bf16(uu[6], uu[7]);
;                 *(u32x4*)(U + (size_t)row * 1024 + dir * 512 + cbase) = w; }
	v_exp_f32_e32 v98, v98
	v_exp_f32_e32 v31, v31
	v_exp_f32_e32 v27, v27
	v_add_f32_e32 v20, v20, v159
	v_sub_f32_e32 v98, 1.0, v98
	v_max_f32_e32 v98, 0, v98
	v_cmp_gt_f32_e32 vcc, s17, v98
	v_mul_f32_e32 v100, 0x4f800000, v98
	v_add_f32_e32 v31, 1.0, v31
	v_cndmask_b32_e32 v98, v98, v100, vcc
	v_sqrt_f32_e32 v100, v98
	v_add_f32_e32 v27, 1.0, v27
	v_mul_f32_e32 v20, 0xbfb8aa3b, v20
	v_exp_f32_e32 v20, v20
	v_add_u32_e32 v105, -1, v100
	v_fma_f32 v120, -v105, v100, v98
	v_cmp_ge_f32_e64 s[2:3], 0, v120
	v_add_u32_e32 v120, 1, v100
	v_add_f32_e32 v20, 1.0, v20
	v_cndmask_b32_e64 v105, v100, v105, s[2:3]
	v_fma_f32 v100, -v120, v100, v98
	v_cmp_lt_f32_e64 s[2:3], 0, v100
	v_rcp_f32_e64 v20, -v20
	v_add_f32_e32 v16, v16, v158
	v_cndmask_b32_e64 v100, v105, v120, s[2:3]
	v_mul_f32_e32 v105, 0x37800000, v100
	v_cndmask_b32_e32 v100, v100, v105, vcc
	v_cmp_class_f32_e32 vcc, v98, v174
	v_mul_f32_e32 v20, v165, v20
	v_mul_f32_e32 v16, 0xbfb8aa3b, v16
	v_cndmask_b32_e32 v98, v100, v98, vcc
	v_mul_f32_e32 v98, v99, v98
	v_mul_f32_e32 v116, v98, v116
	v_cvt_pk_bf16_f32 v98, v106, v107
	v_cvt_pk_bf16_f32 v99, v108, v109
	v_cvt_pk_bf16_f32 v100, v102, v103
	v_lshlrev_b64 v[102:103], 11, v[114:115]
	v_cvt_pk_bf16_f32 v101, v104, v101
	v_lshl_add_u64 v[104:105], s[76:77], 0, v[102:103]
	v_lshl_add_u64 v[104:105], v[104:105], 0, s[64:65]
	v_lshl_add_u64 v[102:103], s[56:57], 0, v[102:103]
	v_lshl_add_u64 v[104:105], v[104:105], 0, v[142:143]
	v_lshl_add_u64 v[102:103], v[102:103], 0, s[64:65]
	global_store_dwordx4 v[104:105], v[98:101], off
	v_lshl_add_u64 v[102:103], v[102:103], 0, v[142:143]
	v_exp_f32_e32 v16, v16
	v_cvt_pk_bf16_f32 v98, v110, v111
	v_cvt_pk_bf16_f32 v99, v112, v113
	v_cvt_pk_bf16_f32 v100, v119, v118
	v_cvt_pk_bf16_f32 v101, v117, v116
	global_store_dwordx4 v[102:103], v[98:101], off
	v_add_f32_e32 v16, 1.0, v16
	v_rcp_f32_e32 v16, v16
	v_add_u32_e32 v98, 32, v144
	v_ashrrev_i32_e32 v99, 31, v98
	v_lshlrev_b64 v[100:101], 10, v[98:99]
	v_lshl_add_u64 v[100:101], s[4:5], 0, v[100:101]
	v_lshl_add_u64 v[100:101], v[100:101], 0, v[142:143]
	s_nop 0
	v_add_f32_e32 v17, v17, v156
	v_mul_f32_e32 v17, 0xbfb8aa3b, v17
	v_exp_f32_e32 v17, v17
	v_add_f32_e32 v12, v12, v173
	v_add_f32_e32 v8, v8, v170
	v_mul_f32_e32 v12, 0xbfb8aa3b, v12
	v_add_f32_e32 v17, 1.0, v17
	v_rcp_f32_e32 v17, v17
	v_mul_f32_e32 v8, 0xbfb8aa3b, v8
	v_exp_f32_e32 v12, v12
	v_exp_f32_e32 v8, v8
	v_add_f32_e32 v13, v13, v168
	v_add_f32_e32 v9, v9, v166
	v_add_f32_e32 v12, 1.0, v12
	v_add_f32_e32 v8, 1.0, v8
	v_mul_f32_e32 v13, 0xbfb8aa3b, v13
	v_mul_f32_e32 v9, 0xbfb8aa3b, v9
	v_exp_f32_e32 v13, v13
	v_exp_f32_e32 v9, v9
	v_add_f32_e32 v14, v14, v164
	v_add_f32_e32 v10, v10, v163
	v_add_f32_e32 v13, 1.0, v13
	v_add_f32_e32 v9, 1.0, v9
	v_mul_f32_e32 v14, 0xbfb8aa3b, v14
	v_mul_f32_e32 v10, 0xbfb8aa3b, v10
	v_exp_f32_e32 v14, v14
	v_exp_f32_e32 v10, v10
	v_add_f32_e32 v15, v15, v162
	v_add_f32_e32 v11, v11, v161
	v_add_f32_e32 v14, 1.0, v14
	v_add_f32_e32 v10, 1.0, v10
	v_mul_f32_e32 v15, 0xbfb8aa3b, v15
	v_mul_f32_e32 v11, 0xbfb8aa3b, v11
	v_exp_f32_e32 v15, v15
	v_exp_f32_e32 v11, v11
	v_add_f32_e32 v4, v4, v159
	v_mul_f32_e32 v4, 0xbfb8aa3b, v4
	v_add_f32_e32 v15, 1.0, v15
	v_add_f32_e32 v11, 1.0, v11
	v_exp_f32_e32 v4, v4
	v_add_f32_e32 v0, v0, v158
	v_mul_f32_e32 v0, 0xbfb8aa3b, v0
	v_exp_f32_e32 v0, v0
	v_add_f32_e32 v4, 1.0, v4
	v_rcp_f32_e64 v4, -v4
	v_add_f32_e32 v1, v1, v156
	v_add_f32_e32 v0, 1.0, v0
	v_rcp_f32_e32 v0, v0
	v_mul_f32_e32 v4, v165, v4
	v_mul_f32_e32 v1, 0xbfb8aa3b, v1
	v_exp_f32_e32 v1, v1
	v_lshlrev_b32_e32 v108, 16, v212
	v_and_b32_e32 v109, 0xffff0000, v212
	v_lshlrev_b32_e32 v110, 16, v213
	v_and_b32_e32 v104, 0xffff0000, v213
	v_rcp_f32_e32 v105, v90
	v_rcp_f32_e64 v90, -v94
	v_lshlrev_b32_e32 v103, 16, v214
	v_and_b32_e32 v102, 0xffff0000, v214
	v_lshlrev_b32_e32 v101, 16, v215
	v_mul_f32_e32 v90, v183, v90
	v_add_f32_e32 v94, v90, v90
	v_exp_f32_e32 v94, v94
	v_and_b32_e32 v100, 0xffff0000, v215
	v_add_f32_e32 v1, 1.0, v1
	v_rcp_f32_e32 v1, v1
	v_sub_f32_e32 v94, 1.0, v94
	v_max_f32_e32 v94, 0, v94
	v_cmp_gt_f32_e32 vcc, s17, v94
	v_mul_f32_e32 v106, 0x4f800000, v94
	s_nop 0
	v_cndmask_b32_e32 v94, v94, v106, vcc
	v_sqrt_f32_e32 v106, v94
	s_nop 0
	v_add_u32_e32 v107, -1, v106
	v_fma_f32 v111, -v107, v106, v94
	v_cmp_ge_f32_e64 s[2:3], 0, v111
	v_add_u32_e32 v111, 1, v106
	s_nop 0
	v_cndmask_b32_e64 v107, v106, v107, s[2:3]
	v_fma_f32 v106, -v111, v106, v94
	v_cmp_lt_f32_e64 s[2:3], 0, v106
	s_nop 1
	v_cndmask_b32_e64 v106, v107, v111, s[2:3]
	v_mul_f32_e32 v107, 0x37800000, v106
	v_cndmask_b32_e32 v106, v106, v107, vcc
	v_cmp_class_f32_e32 vcc, v94, v174
	s_nop 1
	v_cndmask_b32_e32 v94, v106, v94, vcc
	v_mul_f32_e32 v94, v105, v94
	v_rcp_f32_e32 v105, v91
	v_rcp_f32_e64 v91, -v95
	v_mul_f32_e32 v94, v94, v108
	v_mul_f32_e32 v91, v182, v91
	v_add_f32_e32 v95, v91, v91
	v_exp_f32_e32 v95, v95
	s_nop 0
	v_sub_f32_e32 v95, 1.0, v95
	v_max_f32_e32 v95, 0, v95
	v_cmp_gt_f32_e32 vcc, s17, v95
	v_mul_f32_e32 v106, 0x4f800000, v95
	s_nop 0
	v_cndmask_b32_e32 v95, v95, v106, vcc
	v_sqrt_f32_e32 v106, v95
	s_nop 0
	v_add_u32_e32 v107, -1, v106
	v_fma_f32 v108, -v107, v106, v95
	v_cmp_ge_f32_e64 s[2:3], 0, v108
	v_add_u32_e32 v108, 1, v106
	s_nop 0
	v_cndmask_b32_e64 v107, v106, v107, s[2:3]
	v_fma_f32 v106, -v108, v106, v95
	v_cmp_lt_f32_e64 s[2:3], 0, v106
	s_nop 1
	v_cndmask_b32_e64 v106, v107, v108, s[2:3]
	v_mul_f32_e32 v107, 0x37800000, v106
	v_cndmask_b32_e32 v106, v106, v107, vcc
	v_cmp_class_f32_e32 vcc, v95, v174
	s_nop 1
	v_cndmask_b32_e32 v95, v106, v95, vcc
	v_mul_f32_e32 v95, v105, v95
	v_rcp_f32_e32 v105, v92
	v_rcp_f32_e64 v92, -v96
; __device__ __forceinline__ float sigmoidf_(float x) { return __builtin_amdgcn_rcpf(1.0f + __builtin_amdgcn_exp2f(-x * LOG2E)); }
;     __device__ __forceinline__ void operator()(const f32x4 (&acc)[2][2][4][2], const Unit& u, int wr, int wc, int fr, int fq, const float (&rs)[2][4]) const {
;     ...
;                 for (int j = 0; j < 8; ++j) { const float r = sigmoidf_(acc[ai][0][m][j >> 2][j & 3] + ba[j]), ig = sigmoidf_(acc[ai][1][m][j >> 2][j & 3] + bx[j]);
;                     la[j] = -r * sp[j]; const float a2 = __builtin_amdgcn_exp2f(2.0f * la[j]); uu[j] = __builtin_sqrtf(fmaxf(1.0f - a2, 0.0f)) * ig * xc[j]; }
	v_mul_f32_e32 v95, v95, v109
	v_mul_f32_e32 v92, v181, v92
	v_add_f32_e32 v96, v92, v92
	v_exp_f32_e32 v96, v96
	s_nop 0
	v_sub_f32_e32 v96, 1.0, v96
	v_max_f32_e32 v96, 0, v96
	v_cmp_gt_f32_e32 vcc, s17, v96
	v_mul_f32_e32 v106, 0x4f800000, v96
	s_nop 0
	v_cndmask_b32_e32 v96, v96, v106, vcc
	v_sqrt_f32_e32 v106, v96
	s_nop 0
	v_add_u32_e32 v107, -1, v106
	v_fma_f32 v108, -v107, v106, v96
	v_cmp_ge_f32_e64 s[2:3], 0, v108
	v_add_u32_e32 v108, 1, v106
	s_nop 0
	v_cndmask_b32_e64 v107, v106, v107, s[2:3]
	v_fma_f32 v106, -v108, v106, v96
	v_cmp_lt_f32_e64 s[2:3], 0, v106
	s_nop 1
	v_cndmask_b32_e64 v106, v107, v108, s[2:3]
	v_mul_f32_e32 v107, 0x37800000, v106
	v_cndmask_b32_e32 v106, v106, v107, vcc
	v_cmp_class_f32_e32 vcc, v96, v174
	s_nop 1
	v_cndmask_b32_e32 v96, v106, v96, vcc
	v_mul_f32_e32 v96, v105, v96
	v_rcp_f32_e32 v105, v93
	v_rcp_f32_e64 v93, -v97
	v_mul_f32_e32 v96, v96, v110
	v_mul_f32_e32 v93, v172, v93
	v_add_f32_e32 v97, v93, v93
	v_exp_f32_e32 v97, v97
	s_nop 0
	v_sub_f32_e32 v97, 1.0, v97
	v_max_f32_e32 v97, 0, v97
	v_cmp_gt_f32_e32 vcc, s17, v97
	v_mul_f32_e32 v106, 0x4f800000, v97
	s_nop 0
	v_cndmask_b32_e32 v97, v97, v106, vcc
	v_sqrt_f32_e32 v106, v97
	s_nop 0
	v_add_u32_e32 v107, -1, v106
	v_fma_f32 v108, -v107, v106, v97
	v_cmp_ge_f32_e64 s[2:3], 0, v108
	v_add_u32_e32 v108, 1, v106
	s_nop 0
	v_cndmask_b32_e64 v107, v106, v107, s[2:3]
	v_fma_f32 v106, -v108, v106, v97
	v_cmp_lt_f32_e64 s[2:3], 0, v106
	s_nop 1
	v_cndmask_b32_e64 v106, v107, v108, s[2:3]
	v_mul_f32_e32 v107, 0x37800000, v106
	v_cndmask_b32_e32 v106, v106, v107, vcc
	v_cmp_class_f32_e32 vcc, v97, v174
	s_nop 1
	v_cndmask_b32_e32 v97, v106, v97, vcc
	v_mul_f32_e32 v97, v105, v97
	v_mul_f32_e32 v97, v97, v104
	v_add_f32_e32 v104, v86, v86
	v_exp_f32_e32 v104, v104
	s_nop 0
	v_sub_f32_e32 v104, 1.0, v104
	v_max_f32_e32 v104, 0, v104
	v_cmp_gt_f32_e32 vcc, s17, v104
	v_mul_f32_e32 v105, 0x4f800000, v104
	s_nop 0
	v_cndmask_b32_e32 v104, v104, v105, vcc
	v_sqrt_f32_e32 v105, v104
	s_nop 0
	v_add_u32_e32 v106, -1, v105
	v_fma_f32 v107, -v106, v105, v104
	v_cmp_ge_f32_e64 s[2:3], 0, v107
	v_add_u32_e32 v107, 1, v105
	s_nop 0
	v_cndmask_b32_e64 v106, v105, v106, s[2:3]
	v_fma_f32 v105, -v107, v105, v104
	v_cmp_lt_f32_e64 s[2:3], 0, v105
	s_nop 1
	v_cndmask_b32_e64 v105, v106, v107, s[2:3]
	v_mul_f32_e32 v106, 0x37800000, v105
	v_cndmask_b32_e32 v105, v105, v106, vcc
	v_cmp_class_f32_e32 vcc, v104, v174
	s_nop 1
	v_cndmask_b32_e32 v104, v105, v104, vcc
	v_mul_f32_e32 v82, v82, v104
	v_mul_f32_e32 v103, v82, v103
	v_add_f32_e32 v82, v87, v157
	v_mul_f32_e32 v82, 0xbfb8aa3b, v82
	v_exp_f32_e32 v82, v82
	s_nop 0
	v_add_f32_e32 v82, 1.0, v82
	v_rcp_f32_e64 v82, -v82
	s_nop 0
	v_mul_f32_e32 v87, v160, v82
	v_add_f32_e32 v82, v87, v87
	v_exp_f32_e32 v82, v82
	s_nop 0
	v_sub_f32_e32 v82, 1.0, v82
	v_max_f32_e32 v82, 0, v82
	v_cmp_gt_f32_e32 vcc, s17, v82
	v_mul_f32_e32 v104, 0x4f800000, v82
	s_nop 0
	v_cndmask_b32_e32 v82, v82, v104, vcc
	v_sqrt_f32_e32 v104, v82
	s_nop 0
	v_add_u32_e32 v105, -1, v104
	v_fma_f32 v106, -v105, v104, v82
	v_cmp_ge_f32_e64 s[2:3], 0, v106
	v_add_u32_e32 v106, 1, v104
	s_nop 0
	v_cndmask_b32_e64 v105, v104, v105, s[2:3]
	v_fma_f32 v104, -v106, v104, v82
	v_cmp_lt_f32_e64 s[2:3], 0, v104
	s_nop 1
	v_cndmask_b32_e64 v104, v105, v106, s[2:3]
	v_mul_f32_e32 v105, 0x37800000, v104
	v_cndmask_b32_e32 v104, v104, v105, vcc
	v_cmp_class_f32_e32 vcc, v82, v174
	s_nop 1
	v_cndmask_b32_e32 v82, v104, v82, vcc
	v_mul_f32_e32 v82, v83, v82
	v_mul_f32_e32 v102, v82, v102
	v_add_f32_e32 v82, v88, v155
	v_mul_f32_e32 v82, 0xbfb8aa3b, v82
	v_exp_f32_e32 v82, v82
	v_add_f32_e32 v83, v84, v154
	v_mul_f32_e32 v83, 0xbfb8aa3b, v83
	v_exp_f32_e32 v83, v83
	v_add_f32_e32 v82, 1.0, v82
	v_rcp_f32_e64 v82, -v82
	v_add_f32_e32 v83, 1.0, v83
	v_rcp_f32_e32 v83, v83
	v_mul_f32_e32 v88, v149, v82
	v_add_f32_e32 v82, v88, v88
	v_exp_f32_e32 v82, v82
	s_nop 0
	v_sub_f32_e32 v82, 1.0, v82
	v_max_f32_e32 v82, 0, v82
	v_cmp_gt_f32_e32 vcc, s17, v82
	v_mul_f32_e32 v84, 0x4f800000, v82
	s_nop 0
	v_cndmask_b32_e32 v82, v82, v84, vcc
	v_sqrt_f32_e32 v84, v82
	s_nop 0
	v_add_u32_e32 v104, -1, v84
	v_fma_f32 v105, -v104, v84, v82
	v_cmp_ge_f32_e64 s[2:3], 0, v105
	v_add_u32_e32 v105, 1, v84
	s_nop 0
	v_cndmask_b32_e64 v104, v84, v104, s[2:3]
	v_fma_f32 v84, -v105, v84, v82
	v_cmp_lt_f32_e64 s[2:3], 0, v84
	s_nop 1
	v_cndmask_b32_e64 v84, v104, v105, s[2:3]
	v_mul_f32_e32 v104, 0x37800000, v84
	v_cndmask_b32_e32 v84, v84, v104, vcc
	v_cmp_class_f32_e32 vcc, v82, v174
	s_nop 1
	v_cndmask_b32_e32 v82, v84, v82, vcc
	v_mul_f32_e32 v82, v83, v82
	v_mul_f32_e32 v101, v82, v101
	v_add_f32_e32 v82, v89, v147
	v_mul_f32_e32 v82, 0xbfb8aa3b, v82
	v_exp_f32_e32 v82, v82
	v_add_f32_e32 v83, v85, v146
	v_mul_f32_e32 v83, 0xbfb8aa3b, v83
	v_exp_f32_e32 v83, v83
	v_add_f32_e32 v82, 1.0, v82
	v_rcp_f32_e64 v82, -v82
	v_add_f32_e32 v83, 1.0, v83
	v_rcp_f32_e32 v83, v83
	v_mul_f32_e32 v85, v148, v82
	v_add_f32_e32 v82, v85, v85
	v_exp_f32_e32 v82, v82
	s_nop 0
	v_sub_f32_e32 v82, 1.0, v82
	v_max_f32_e32 v82, 0, v82
	v_cmp_gt_f32_e32 vcc, s17, v82
	v_mul_f32_e32 v84, 0x4f800000, v82
	s_nop 0
	v_cndmask_b32_e32 v82, v82, v84, vcc
	v_sqrt_f32_e32 v84, v82
	s_nop 0
	v_add_u32_e32 v89, -1, v84
	v_fma_f32 v104, -v89, v84, v82
	v_cmp_ge_f32_e64 s[2:3], 0, v104
	v_add_u32_e32 v104, 1, v84
	s_nop 0
	v_cndmask_b32_e64 v89, v84, v89, s[2:3]
	v_fma_f32 v84, -v104, v84, v82
	v_cmp_lt_f32_e64 s[2:3], 0, v84
	s_nop 1
	v_cndmask_b32_e64 v84, v89, v104, s[2:3]
	v_mul_f32_e32 v89, 0x37800000, v84
	v_cndmask_b32_e32 v84, v84, v89, vcc
	v_cmp_class_f32_e32 vcc, v82, v174
	s_nop 1
	v_cndmask_b32_e32 v82, v84, v82, vcc
; __device__ __forceinline__ unsigned cvt_pk_bf16(float lo, float hi) { unsigned r; asm volatile("v_cvt_pk_bf16_f32 %0, %1, %2" : "=v"(r) : "v"(lo), "v"(hi)); return r; }
; __device__ __forceinline__ float bf_lo(unsigned w) { return __uint_as_float(w << 16); }
; __device__ __forceinline__ float bf_hi(unsigned w) { return __uint_as_float(w & 0xffff0000u); }
; __device__ __forceinline__ float sigmoidf_(float x) { return __builtin_amdgcn_rcpf(1.0f + __builtin_amdgcn_exp2f(-x * LOG2E)); }
;     __device__ __forceinline__ void operator()(const f32x4 (&acc)[2][2][4][2], const Unit& u, int wr, int wc, int fr, int fq, const float (&rs)[2][4]) const {
;     ...
;             for (int m = 0; m < 4; ++m) { const int row = row0 + ai * HALF + m * 16;
;                 const u32x4 xw = *(const u32x4*)(XC + (size_t)row * 512 + cbase);
;                 float xc[8] = {bf_lo(xw.x), bf_hi(xw.x), bf_lo(xw.y), bf_hi(xw.y), bf_lo(xw.z), bf_hi(xw.z), bf_lo(xw.w), bf_hi(xw.w)};
;                 float la[8], uu[8];
; #pragma unroll
;                 for (int j = 0; j < 8; ++j) { const float r = sigmoidf_(acc[ai][0][m][j >> 2][j & 3] + ba[j]), ig = sigmoidf_(acc[ai][1][m][j >> 2][j & 3] + bx[j]);
;                     la[j] = -r * sp[j]; const float a2 = __builtin_amdgcn_exp2f(2.0f * la[j]); uu[j] = __builtin_sqrtf(fmaxf(1.0f - a2, 0.0f)) * ig * xc[j]; }
;                 u32x4 w; w.x = cvt_pk_bf16(la[0], la[1]); w.y = cvt_pk_bf16(la[2], la[3]); w.z = cvt_pk_bf16(la[4], la[5]); w.w = cvt_pk_bf16(la[6], la[7]);
;                 *(u32x4*)(LA + (size_t)row * 1024 + dir * 512 + cbase) = w;
;                 w.x = cvt_pk_bf16(uu[0], uu[1]); w.y = cvt_pk_bf16(uu[2], uu[3]); w.z = cvt_pk_bf16(uu[4], uu[5]); w.w = cvt_pk_bf16(uu[6], uu[7]);
;                 *(u32x4*)(U + (size_t)row * 1024 + dir * 512 + cbase) = w; }
	v_mul_f32_e32 v82, v83, v82
	v_mul_f32_e32 v100, v82, v100
	v_cvt_pk_bf16_f32 v82, v90, v91
	v_cvt_pk_bf16_f32 v83, v92, v93
	v_cvt_pk_bf16_f32 v84, v86, v87
	v_lshlrev_b64 v[86:87], 11, v[98:99]
	v_cvt_pk_bf16_f32 v85, v88, v85
	v_lshl_add_u64 v[88:89], s[76:77], 0, v[86:87]
	v_lshl_add_u64 v[88:89], v[88:89], 0, s[64:65]
	v_lshl_add_u64 v[86:87], s[56:57], 0, v[86:87]
	v_lshl_add_u64 v[88:89], v[88:89], 0, v[142:143]
	v_lshl_add_u64 v[86:87], v[86:87], 0, s[64:65]
	global_store_dwordx4 v[88:89], v[82:85], off
	v_lshl_add_u64 v[86:87], v[86:87], 0, v[142:143]
	s_nop 0
	v_cvt_pk_bf16_f32 v82, v94, v95
	v_cvt_pk_bf16_f32 v83, v96, v97
	v_cvt_pk_bf16_f32 v84, v103, v102
	v_cvt_pk_bf16_f32 v85, v101, v100
	global_store_dwordx4 v[86:87], v[82:85], off
	s_nop 1
	v_add_u32_e32 v82, 48, v144
	v_ashrrev_i32_e32 v83, 31, v82
	v_lshlrev_b64 v[84:85], 10, v[82:83]
	v_lshl_add_u64 v[84:85], s[4:5], 0, v[84:85]
	v_lshl_add_u64 v[84:85], v[84:85], 0, v[142:143]
	s_nop 0
	v_lshlrev_b32_e32 v92, 16, v216
	v_and_b32_e32 v93, 0xffff0000, v216
	v_lshlrev_b32_e32 v94, 16, v217
	v_and_b32_e32 v88, 0xffff0000, v217
	v_rcp_f32_e32 v89, v72
	v_rcp_f32_e64 v72, -v76
	v_lshlrev_b32_e32 v87, 16, v218
	v_and_b32_e32 v86, 0xffff0000, v218
	v_lshlrev_b32_e32 v85, 16, v219
	v_mul_f32_e32 v72, v183, v72
	v_add_f32_e32 v76, v72, v72
	v_exp_f32_e32 v76, v76
	v_and_b32_e32 v84, 0xffff0000, v219
	v_sub_f32_e32 v76, 1.0, v76
	v_max_f32_e32 v76, 0, v76
	v_cmp_gt_f32_e32 vcc, s17, v76
	v_mul_f32_e32 v90, 0x4f800000, v76
	s_nop 0
	v_cndmask_b32_e32 v76, v76, v90, vcc
	v_sqrt_f32_e32 v90, v76
	s_nop 0
	v_add_u32_e32 v91, -1, v90
	v_fma_f32 v95, -v91, v90, v76
	v_cmp_ge_f32_e64 s[2:3], 0, v95
	v_add_u32_e32 v95, 1, v90
	s_nop 0
	v_cndmask_b32_e64 v91, v90, v91, s[2:3]
	v_fma_f32 v90, -v95, v90, v76
	v_cmp_lt_f32_e64 s[2:3], 0, v90
	s_nop 1
	v_cndmask_b32_e64 v90, v91, v95, s[2:3]
	v_mul_f32_e32 v91, 0x37800000, v90
	v_cndmask_b32_e32 v90, v90, v91, vcc
	v_cmp_class_f32_e32 vcc, v76, v174
	s_nop 1
	v_cndmask_b32_e32 v76, v90, v76, vcc
	v_mul_f32_e32 v76, v89, v76
	v_rcp_f32_e32 v89, v73
	v_rcp_f32_e64 v73, -v77
	v_mul_f32_e32 v76, v76, v92
	v_mul_f32_e32 v73, v182, v73
	v_add_f32_e32 v77, v73, v73
	v_exp_f32_e32 v77, v77
	s_nop 0
	v_sub_f32_e32 v77, 1.0, v77
	v_max_f32_e32 v77, 0, v77
	v_cmp_gt_f32_e32 vcc, s17, v77
	v_mul_f32_e32 v90, 0x4f800000, v77
	s_nop 0
	v_cndmask_b32_e32 v77, v77, v90, vcc
	v_sqrt_f32_e32 v90, v77
	s_nop 0
	v_add_u32_e32 v91, -1, v90
	v_fma_f32 v92, -v91, v90, v77
	v_cmp_ge_f32_e64 s[2:3], 0, v92
	v_add_u32_e32 v92, 1, v90
	s_nop 0
	v_cndmask_b32_e64 v91, v90, v91, s[2:3]
	v_fma_f32 v90, -v92, v90, v77
	v_cmp_lt_f32_e64 s[2:3], 0, v90
	s_nop 1
	v_cndmask_b32_e64 v90, v91, v92, s[2:3]
	v_mul_f32_e32 v91, 0x37800000, v90
	v_cndmask_b32_e32 v90, v90, v91, vcc
	v_cmp_class_f32_e32 vcc, v77, v174
	s_nop 1
	v_cndmask_b32_e32 v77, v90, v77, vcc
	v_mul_f32_e32 v77, v89, v77
	v_rcp_f32_e32 v89, v74
	v_rcp_f32_e64 v74, -v78
	v_mul_f32_e32 v77, v77, v93
	v_mul_f32_e32 v74, v181, v74
	v_add_f32_e32 v78, v74, v74
	v_exp_f32_e32 v78, v78
	s_nop 0
	v_sub_f32_e32 v78, 1.0, v78
	v_max_f32_e32 v78, 0, v78
	v_cmp_gt_f32_e32 vcc, s17, v78
	v_mul_f32_e32 v90, 0x4f800000, v78
	s_nop 0
	v_cndmask_b32_e32 v78, v78, v90, vcc
	v_sqrt_f32_e32 v90, v78
	s_nop 0
	v_add_u32_e32 v91, -1, v90
	v_fma_f32 v92, -v91, v90, v78
	v_cmp_ge_f32_e64 s[2:3], 0, v92
	v_add_u32_e32 v92, 1, v90
	s_nop 0
	v_cndmask_b32_e64 v91, v90, v91, s[2:3]
	v_fma_f32 v90, -v92, v90, v78
	v_cmp_lt_f32_e64 s[2:3], 0, v90
	s_nop 1
	v_cndmask_b32_e64 v90, v91, v92, s[2:3]
	v_mul_f32_e32 v91, 0x37800000, v90
	v_cndmask_b32_e32 v90, v90, v91, vcc
	v_cmp_class_f32_e32 vcc, v78, v174
	s_nop 1
	v_cndmask_b32_e32 v78, v90, v78, vcc
	v_mul_f32_e32 v78, v89, v78
	v_rcp_f32_e32 v89, v75
	v_rcp_f32_e64 v75, -v79
	v_mul_f32_e32 v78, v78, v94
	v_mul_f32_e32 v75, v172, v75
	v_add_f32_e32 v79, v75, v75
	v_exp_f32_e32 v79, v79
	s_nop 0
	v_sub_f32_e32 v79, 1.0, v79
	v_max_f32_e32 v79, 0, v79
	v_cmp_gt_f32_e32 vcc, s17, v79
	v_mul_f32_e32 v90, 0x4f800000, v79
	s_nop 0
	v_cndmask_b32_e32 v79, v79, v90, vcc
	v_sqrt_f32_e32 v90, v79
	s_nop 0
	v_add_u32_e32 v91, -1, v90
	v_fma_f32 v92, -v91, v90, v79
	v_cmp_ge_f32_e64 s[2:3], 0, v92
	v_add_u32_e32 v92, 1, v90
	s_nop 0
	v_cndmask_b32_e64 v91, v90, v91, s[2:3]
	v_fma_f32 v90, -v92, v90, v79
	v_cmp_lt_f32_e64 s[2:3], 0, v90
	s_nop 1
	v_cndmask_b32_e64 v90, v91, v92, s[2:3]
	v_mul_f32_e32 v91, 0x37800000, v90
	v_cndmask_b32_e32 v90, v90, v91, vcc
	v_cmp_class_f32_e32 vcc, v79, v174
	s_nop 1
	v_cndmask_b32_e32 v79, v90, v79, vcc
	v_mul_f32_e32 v79, v89, v79
	v_mul_f32_e32 v79, v79, v88
	v_add_f32_e32 v88, v68, v68
	v_exp_f32_e32 v88, v88
	s_nop 0
	v_sub_f32_e32 v88, 1.0, v88
	v_max_f32_e32 v88, 0, v88
	v_cmp_gt_f32_e32 vcc, s17, v88
	v_mul_f32_e32 v89, 0x4f800000, v88
	s_nop 0
	v_cndmask_b32_e32 v88, v88, v89, vcc
	v_sqrt_f32_e32 v89, v88
	s_nop 0
	v_add_u32_e32 v90, -1, v89
	v_fma_f32 v91, -v90, v89, v88
	v_cmp_ge_f32_e64 s[2:3], 0, v91
	v_add_u32_e32 v91, 1, v89
	s_nop 0
	v_cndmask_b32_e64 v90, v89, v90, s[2:3]
	v_fma_f32 v89, -v91, v89, v88
	v_cmp_lt_f32_e64 s[2:3], 0, v89
	s_nop 1
	v_cndmask_b32_e64 v89, v90, v91, s[2:3]
	v_mul_f32_e32 v90, 0x37800000, v89
	v_cndmask_b32_e32 v89, v89, v90, vcc
	v_cmp_class_f32_e32 vcc, v88, v174
	s_nop 1
	v_cndmask_b32_e32 v88, v89, v88, vcc
	v_mul_f32_e32 v64, v64, v88
	v_mul_f32_e32 v87, v64, v87
	v_add_f32_e32 v64, v69, v157
	v_mul_f32_e32 v64, 0xbfb8aa3b, v64
	v_exp_f32_e32 v64, v64
	s_nop 0
	v_add_f32_e32 v64, 1.0, v64
	v_rcp_f32_e64 v64, -v64
	s_nop 0
	v_mul_f32_e32 v69, v160, v64
	v_add_f32_e32 v64, v69, v69
	v_exp_f32_e32 v64, v64
	s_nop 0
; __device__ __forceinline__ unsigned cvt_pk_bf16(float lo, float hi) { unsigned r; asm volatile("v_cvt_pk_bf16_f32 %0, %1, %2" : "=v"(r) : "v"(lo), "v"(hi)); return r; }
; __device__ __forceinline__ float bf_lo(unsigned w) { return __uint_as_float(w << 16); }
; __device__ __forceinline__ float bf_hi(unsigned w) { return __uint_as_float(w & 0xffff0000u); }
; __device__ __forceinline__ float sigmoidf_(float x) { return __builtin_amdgcn_rcpf(1.0f + __builtin_amdgcn_exp2f(-x * LOG2E)); }
;     __device__ __forceinline__ void operator()(const f32x4 (&acc)[2][2][4][2], const Unit& u, int wr, int wc, int fr, int fq, const float (&rs)[2][4]) const {
;     ...
;             for (int m = 0; m < 4; ++m) { const int row = row0 + ai * HALF + m * 16;
;                 const u32x4 xw = *(const u32x4*)(XC + (size_t)row * 512 + cbase);
;                 float xc[8] = {bf_lo(xw.x), bf_hi(xw.x), bf_lo(xw.y), bf_hi(xw.y), bf_lo(xw.z), bf_hi(xw.z), bf_lo(xw.w), bf_hi(xw.w)};
;                 float la[8], uu[8];
; #pragma unroll
;                 for (int j = 0; j < 8; ++j) { const float r = sigmoidf_(acc[ai][0][m][j >> 2][j & 3] + ba[j]), ig = sigmoidf_(acc[ai][1][m][j >> 2][j & 3] + bx[j]);
;                     la[j] = -r * sp[j]; const float a2 = __builtin_amdgcn_exp2f(2.0f * la[j]); uu[j] = __builtin_sqrtf(fmaxf(1.0f - a2, 0.0f)) * ig * xc[j]; }
;                 u32x4 w; w.x = cvt_pk_bf16(la[0], la[1]); w.y = cvt_pk_bf16(la[2], la[3]); w.z = cvt_pk_bf16(la[4], la[5]); w.w = cvt_pk_bf16(la[6], la[7]);
;                 *(u32x4*)(LA + (size_t)row * 1024 + dir * 512 + cbase) = w;
;                 w.x = cvt_pk_bf16(uu[0], uu[1]); w.y = cvt_pk_bf16(uu[2], uu[3]); w.z = cvt_pk_bf16(uu[4], uu[5]); w.w = cvt_pk_bf16(uu[6], uu[7]);
;                 *(u32x4*)(U + (size_t)row * 1024 + dir * 512 + cbase) = w; }
	v_sub_f32_e32 v64, 1.0, v64
	v_max_f32_e32 v64, 0, v64
	v_cmp_gt_f32_e32 vcc, s17, v64
	v_mul_f32_e32 v88, 0x4f800000, v64
	s_nop 0
	v_cndmask_b32_e32 v64, v64, v88, vcc
	v_sqrt_f32_e32 v88, v64
	s_nop 0
	v_add_u32_e32 v89, -1, v88
	v_fma_f32 v90, -v89, v88, v64
	v_cmp_ge_f32_e64 s[2:3], 0, v90
	v_add_u32_e32 v90, 1, v88
	s_nop 0
	v_cndmask_b32_e64 v89, v88, v89, s[2:3]
	v_fma_f32 v88, -v90, v88, v64
	v_cmp_lt_f32_e64 s[2:3], 0, v88
	s_nop 1
	v_cndmask_b32_e64 v88, v89, v90, s[2:3]
	v_mul_f32_e32 v89, 0x37800000, v88
	v_cndmask_b32_e32 v88, v88, v89, vcc
	v_cmp_class_f32_e32 vcc, v64, v174
	s_nop 1
	v_cndmask_b32_e32 v64, v88, v64, vcc
	v_mul_f32_e32 v64, v65, v64
	v_mul_f32_e32 v86, v64, v86
	v_add_f32_e32 v64, v70, v155
	v_mul_f32_e32 v64, 0xbfb8aa3b, v64
	v_exp_f32_e32 v64, v64
	v_add_f32_e32 v65, v66, v154
	v_mul_f32_e32 v65, 0xbfb8aa3b, v65
	v_exp_f32_e32 v65, v65
	v_add_f32_e32 v64, 1.0, v64
	v_rcp_f32_e64 v64, -v64
	v_add_f32_e32 v65, 1.0, v65
	v_rcp_f32_e32 v65, v65
	v_mul_f32_e32 v70, v149, v64
	v_add_f32_e32 v64, v70, v70
	v_exp_f32_e32 v64, v64
	s_nop 0
	v_sub_f32_e32 v64, 1.0, v64
	v_max_f32_e32 v64, 0, v64
	v_cmp_gt_f32_e32 vcc, s17, v64
	v_mul_f32_e32 v66, 0x4f800000, v64
	s_nop 0
	v_cndmask_b32_e32 v64, v64, v66, vcc
	v_sqrt_f32_e32 v66, v64
	s_nop 0
	v_add_u32_e32 v88, -1, v66
	v_fma_f32 v89, -v88, v66, v64
	v_cmp_ge_f32_e64 s[2:3], 0, v89
	v_add_u32_e32 v89, 1, v66
	s_nop 0
	v_cndmask_b32_e64 v88, v66, v88, s[2:3]
	v_fma_f32 v66, -v89, v66, v64
	v_cmp_lt_f32_e64 s[2:3], 0, v66
	s_nop 1
	v_cndmask_b32_e64 v66, v88, v89, s[2:3]
	v_mul_f32_e32 v88, 0x37800000, v66
	v_cndmask_b32_e32 v66, v66, v88, vcc
	v_cmp_class_f32_e32 vcc, v64, v174
	s_nop 1
	v_cndmask_b32_e32 v64, v66, v64, vcc
	v_mul_f32_e32 v64, v65, v64
	v_mul_f32_e32 v85, v64, v85
	v_add_f32_e32 v64, v71, v147
	v_mul_f32_e32 v64, 0xbfb8aa3b, v64
	v_exp_f32_e32 v64, v64
	v_add_f32_e32 v65, v67, v146
	v_mul_f32_e32 v65, 0xbfb8aa3b, v65
	v_exp_f32_e32 v65, v65
	v_add_f32_e32 v64, 1.0, v64
	v_rcp_f32_e64 v64, -v64
	v_add_f32_e32 v65, 1.0, v65
	v_rcp_f32_e32 v65, v65
	v_mul_f32_e32 v67, v148, v64
	v_add_f32_e32 v64, v67, v67
	v_exp_f32_e32 v64, v64
	s_nop 0
	v_sub_f32_e32 v64, 1.0, v64
	v_max_f32_e32 v64, 0, v64
	v_cmp_gt_f32_e32 vcc, s17, v64
	v_mul_f32_e32 v66, 0x4f800000, v64
	s_nop 0
	v_cndmask_b32_e32 v64, v64, v66, vcc
	v_sqrt_f32_e32 v66, v64
	s_nop 0
	v_add_u32_e32 v71, -1, v66
	v_fma_f32 v88, -v71, v66, v64
	v_cmp_ge_f32_e64 s[2:3], 0, v88
	v_add_u32_e32 v88, 1, v66
	s_nop 0
	v_cndmask_b32_e64 v71, v66, v71, s[2:3]
	v_fma_f32 v66, -v88, v66, v64
	v_cmp_lt_f32_e64 s[2:3], 0, v66
	s_nop 1
	v_cndmask_b32_e64 v66, v71, v88, s[2:3]
	v_mul_f32_e32 v71, 0x37800000, v66
	v_cndmask_b32_e32 v66, v66, v71, vcc
	v_cmp_class_f32_e32 vcc, v64, v174
	s_nop 1
	v_cndmask_b32_e32 v64, v66, v64, vcc
	v_mul_f32_e32 v64, v65, v64
	v_mul_f32_e32 v84, v64, v84
	v_cvt_pk_bf16_f32 v64, v72, v73
	v_cvt_pk_bf16_f32 v65, v74, v75
	v_cvt_pk_bf16_f32 v66, v68, v69
	v_lshlrev_b64 v[68:69], 11, v[82:83]
	v_cvt_pk_bf16_f32 v67, v70, v67
	v_lshl_add_u64 v[70:71], s[76:77], 0, v[68:69]
	v_lshl_add_u64 v[70:71], v[70:71], 0, s[64:65]
	v_lshl_add_u64 v[68:69], s[56:57], 0, v[68:69]
	v_lshl_add_u64 v[70:71], v[70:71], 0, v[142:143]
	v_lshl_add_u64 v[68:69], v[68:69], 0, s[64:65]
	global_store_dwordx4 v[70:71], v[64:67], off
	v_lshl_add_u64 v[68:69], v[68:69], 0, v[142:143]
	s_nop 0
	v_cvt_pk_bf16_f32 v64, v76, v77
	v_cvt_pk_bf16_f32 v65, v78, v79
	v_cvt_pk_bf16_f32 v66, v87, v86
	v_cvt_pk_bf16_f32 v67, v85, v84
	global_store_dwordx4 v[68:69], v[64:67], off
	s_nop 1
	v_add_u32_e32 v64, 0x80, v144
	v_ashrrev_i32_e32 v65, 31, v64
	v_lshlrev_b64 v[66:67], 10, v[64:65]
	v_lshl_add_u64 v[66:67], s[4:5], 0, v[66:67]
	v_lshl_add_u64 v[66:67], v[66:67], 0, v[142:143]
	s_nop 0
	v_lshlrev_b32_e32 v74, 16, v220
	v_and_b32_e32 v75, 0xffff0000, v220
	v_lshlrev_b32_e32 v76, 16, v221
	v_and_b32_e32 v70, 0xffff0000, v221
	v_rcp_f32_e32 v71, v56
	v_rcp_f32_e64 v56, -v60
	v_lshlrev_b32_e32 v69, 16, v222
	v_and_b32_e32 v68, 0xffff0000, v222
	v_lshlrev_b32_e32 v67, 16, v223
	v_mul_f32_e32 v56, v183, v56
	v_add_f32_e32 v60, v56, v56
	v_exp_f32_e32 v60, v60
	v_and_b32_e32 v66, 0xffff0000, v223
	v_sub_f32_e32 v60, 1.0, v60
	v_max_f32_e32 v60, 0, v60
	v_cmp_gt_f32_e32 vcc, s17, v60
	v_mul_f32_e32 v72, 0x4f800000, v60
	s_nop 0
	v_cndmask_b32_e32 v60, v60, v72, vcc
	v_sqrt_f32_e32 v72, v60
	s_nop 0
	v_add_u32_e32 v73, -1, v72
	v_fma_f32 v77, -v73, v72, v60
	v_cmp_ge_f32_e64 s[2:3], 0, v77
	v_add_u32_e32 v77, 1, v72
	s_nop 0
	v_cndmask_b32_e64 v73, v72, v73, s[2:3]
	v_fma_f32 v72, -v77, v72, v60
	v_cmp_lt_f32_e64 s[2:3], 0, v72
	s_nop 1
	v_cndmask_b32_e64 v72, v73, v77, s[2:3]
	v_mul_f32_e32 v73, 0x37800000, v72
	v_cndmask_b32_e32 v72, v72, v73, vcc
	v_cmp_class_f32_e32 vcc, v60, v174
	s_nop 1
	v_cndmask_b32_e32 v60, v72, v60, vcc
	v_mul_f32_e32 v60, v71, v60
	v_rcp_f32_e32 v71, v57
	v_rcp_f32_e64 v57, -v61
	v_mul_f32_e32 v60, v60, v74
	v_mul_f32_e32 v57, v182, v57
	v_add_f32_e32 v61, v57, v57
	v_exp_f32_e32 v61, v61
	s_nop 0
	v_sub_f32_e32 v61, 1.0, v61
	v_max_f32_e32 v61, 0, v61
	v_cmp_gt_f32_e32 vcc, s17, v61
	v_mul_f32_e32 v72, 0x4f800000, v61
	s_nop 0
	v_cndmask_b32_e32 v61, v61, v72, vcc
	v_sqrt_f32_e32 v72, v61
	s_nop 0
	v_add_u32_e32 v73, -1, v72
	v_fma_f32 v74, -v73, v72, v61
	v_cmp_ge_f32_e64 s[2:3], 0, v74
	v_add_u32_e32 v74, 1, v72
	s_nop 0
	v_cndmask_b32_e64 v73, v72, v73, s[2:3]
	v_fma_f32 v72, -v74, v72, v61
	v_cmp_lt_f32_e64 s[2:3], 0, v72
	s_nop 1
	v_cndmask_b32_e64 v72, v73, v74, s[2:3]
	v_mul_f32_e32 v73, 0x37800000, v72
	v_cndmask_b32_e32 v72, v72, v73, vcc
	v_cmp_class_f32_e32 vcc, v61, v174
	s_nop 1
; __device__ __forceinline__ float sigmoidf_(float x) { return __builtin_amdgcn_rcpf(1.0f + __builtin_amdgcn_exp2f(-x * LOG2E)); }
;     __device__ __forceinline__ void operator()(const f32x4 (&acc)[2][2][4][2], const Unit& u, int wr, int wc, int fr, int fq, const float (&rs)[2][4]) const {
;     ...
;                 for (int j = 0; j < 8; ++j) { const float r = sigmoidf_(acc[ai][0][m][j >> 2][j & 3] + ba[j]), ig = sigmoidf_(acc[ai][1][m][j >> 2][j & 3] + bx[j]);
;                     la[j] = -r * sp[j]; const float a2 = __builtin_amdgcn_exp2f(2.0f * la[j]); uu[j] = __builtin_sqrtf(fmaxf(1.0f - a2, 0.0f)) * ig * xc[j]; }
	v_cndmask_b32_e32 v61, v72, v61, vcc
	v_mul_f32_e32 v61, v71, v61
	v_rcp_f32_e32 v71, v58
	v_rcp_f32_e64 v58, -v62
	v_mul_f32_e32 v61, v61, v75
	v_mul_f32_e32 v58, v181, v58
	v_add_f32_e32 v62, v58, v58
	v_exp_f32_e32 v62, v62
	s_nop 0
	v_sub_f32_e32 v62, 1.0, v62
	v_max_f32_e32 v62, 0, v62
	v_cmp_gt_f32_e32 vcc, s17, v62
	v_mul_f32_e32 v72, 0x4f800000, v62
	s_nop 0
	v_cndmask_b32_e32 v62, v62, v72, vcc
	v_sqrt_f32_e32 v72, v62
	s_nop 0
	v_add_u32_e32 v73, -1, v72
	v_fma_f32 v74, -v73, v72, v62
	v_cmp_ge_f32_e64 s[2:3], 0, v74
	v_add_u32_e32 v74, 1, v72
	s_nop 0
	v_cndmask_b32_e64 v73, v72, v73, s[2:3]
	v_fma_f32 v72, -v74, v72, v62
	v_cmp_lt_f32_e64 s[2:3], 0, v72
	s_nop 1
	v_cndmask_b32_e64 v72, v73, v74, s[2:3]
	v_mul_f32_e32 v73, 0x37800000, v72
	v_cndmask_b32_e32 v72, v72, v73, vcc
	v_cmp_class_f32_e32 vcc, v62, v174
	s_nop 1
	v_cndmask_b32_e32 v62, v72, v62, vcc
	v_mul_f32_e32 v62, v71, v62
	v_rcp_f32_e32 v71, v59
	v_rcp_f32_e64 v59, -v63
	v_mul_f32_e32 v62, v62, v76
	v_mul_f32_e32 v59, v172, v59
	v_add_f32_e32 v63, v59, v59
	v_exp_f32_e32 v63, v63
	s_nop 0
	v_sub_f32_e32 v63, 1.0, v63
	v_max_f32_e32 v63, 0, v63
	v_cmp_gt_f32_e32 vcc, s17, v63
	v_mul_f32_e32 v72, 0x4f800000, v63
	s_nop 0
	v_cndmask_b32_e32 v63, v63, v72, vcc
	v_sqrt_f32_e32 v72, v63
	s_nop 0
	v_add_u32_e32 v73, -1, v72
	v_fma_f32 v74, -v73, v72, v63
	v_cmp_ge_f32_e64 s[2:3], 0, v74
	v_add_u32_e32 v74, 1, v72
	s_nop 0
	v_cndmask_b32_e64 v73, v72, v73, s[2:3]
	v_fma_f32 v72, -v74, v72, v63
	v_cmp_lt_f32_e64 s[2:3], 0, v72
	s_nop 1
	v_cndmask_b32_e64 v72, v73, v74, s[2:3]
	v_mul_f32_e32 v73, 0x37800000, v72
	v_cndmask_b32_e32 v72, v72, v73, vcc
	v_cmp_class_f32_e32 vcc, v63, v174
	s_nop 1
	v_cndmask_b32_e32 v63, v72, v63, vcc
	v_mul_f32_e32 v63, v71, v63
	v_mul_f32_e32 v63, v63, v70
	v_add_f32_e32 v70, v52, v52
	v_exp_f32_e32 v70, v70
	s_nop 0
	v_sub_f32_e32 v70, 1.0, v70
	v_max_f32_e32 v70, 0, v70
	v_cmp_gt_f32_e32 vcc, s17, v70
	v_mul_f32_e32 v71, 0x4f800000, v70
	s_nop 0
	v_cndmask_b32_e32 v70, v70, v71, vcc
	v_sqrt_f32_e32 v71, v70
	s_nop 0
	v_add_u32_e32 v72, -1, v71
	v_fma_f32 v73, -v72, v71, v70
	v_cmp_ge_f32_e64 s[2:3], 0, v73
	v_add_u32_e32 v73, 1, v71
	s_nop 0
	v_cndmask_b32_e64 v72, v71, v72, s[2:3]
	v_fma_f32 v71, -v73, v71, v70
	v_cmp_lt_f32_e64 s[2:3], 0, v71
	s_nop 1
	v_cndmask_b32_e64 v71, v72, v73, s[2:3]
	v_mul_f32_e32 v72, 0x37800000, v71
	v_cndmask_b32_e32 v71, v71, v72, vcc
	v_cmp_class_f32_e32 vcc, v70, v174
	s_nop 1
	v_cndmask_b32_e32 v70, v71, v70, vcc
	v_mul_f32_e32 v48, v48, v70
	v_mul_f32_e32 v69, v48, v69
	v_add_f32_e32 v48, v53, v157
	v_mul_f32_e32 v48, 0xbfb8aa3b, v48
	v_exp_f32_e32 v48, v48
	s_nop 0
	v_add_f32_e32 v48, 1.0, v48
	v_rcp_f32_e64 v48, -v48
	s_nop 0
	v_mul_f32_e32 v53, v160, v48
	v_add_f32_e32 v48, v53, v53
	v_exp_f32_e32 v48, v48
	s_nop 0
	v_sub_f32_e32 v48, 1.0, v48
	v_max_f32_e32 v48, 0, v48
	v_cmp_gt_f32_e32 vcc, s17, v48
	v_mul_f32_e32 v70, 0x4f800000, v48
	s_nop 0
	v_cndmask_b32_e32 v48, v48, v70, vcc
	v_sqrt_f32_e32 v70, v48
	s_nop 0
	v_add_u32_e32 v71, -1, v70
	v_fma_f32 v72, -v71, v70, v48
	v_cmp_ge_f32_e64 s[2:3], 0, v72
	v_add_u32_e32 v72, 1, v70
	s_nop 0
	v_cndmask_b32_e64 v71, v70, v71, s[2:3]
	v_fma_f32 v70, -v72, v70, v48
	v_cmp_lt_f32_e64 s[2:3], 0, v70
	s_nop 1
	v_cndmask_b32_e64 v70, v71, v72, s[2:3]
	v_mul_f32_e32 v71, 0x37800000, v70
	v_cndmask_b32_e32 v70, v70, v71, vcc
	v_cmp_class_f32_e32 vcc, v48, v174
	s_nop 1
	v_cndmask_b32_e32 v48, v70, v48, vcc
	v_mul_f32_e32 v48, v49, v48
	v_mul_f32_e32 v68, v48, v68
	v_add_f32_e32 v48, v54, v155
	v_mul_f32_e32 v48, 0xbfb8aa3b, v48
	v_exp_f32_e32 v48, v48
	v_add_f32_e32 v49, v50, v154
	v_mul_f32_e32 v49, 0xbfb8aa3b, v49
	v_exp_f32_e32 v49, v49
	v_add_f32_e32 v48, 1.0, v48
	v_rcp_f32_e64 v48, -v48
	v_add_f32_e32 v49, 1.0, v49
	v_rcp_f32_e32 v49, v49
	v_mul_f32_e32 v54, v149, v48
	v_add_f32_e32 v48, v54, v54
	v_exp_f32_e32 v48, v48
	s_nop 0
	v_sub_f32_e32 v48, 1.0, v48
	v_max_f32_e32 v48, 0, v48
	v_cmp_gt_f32_e32 vcc, s17, v48
	v_mul_f32_e32 v50, 0x4f800000, v48
	s_nop 0
	v_cndmask_b32_e32 v48, v48, v50, vcc
	v_sqrt_f32_e32 v50, v48
	s_nop 0
	v_add_u32_e32 v70, -1, v50
	v_fma_f32 v71, -v70, v50, v48
	v_cmp_ge_f32_e64 s[2:3], 0, v71
	v_add_u32_e32 v71, 1, v50
	s_nop 0
	v_cndmask_b32_e64 v70, v50, v70, s[2:3]
	v_fma_f32 v50, -v71, v50, v48
	v_cmp_lt_f32_e64 s[2:3], 0, v50
	s_nop 1
	v_cndmask_b32_e64 v50, v70, v71, s[2:3]
	v_mul_f32_e32 v70, 0x37800000, v50
	v_cndmask_b32_e32 v50, v50, v70, vcc
	v_cmp_class_f32_e32 vcc, v48, v174
	s_nop 1
	v_cndmask_b32_e32 v48, v50, v48, vcc
	v_mul_f32_e32 v48, v49, v48
	v_mul_f32_e32 v67, v48, v67
	v_add_f32_e32 v48, v55, v147
	v_mul_f32_e32 v48, 0xbfb8aa3b, v48
	v_exp_f32_e32 v48, v48
	v_add_f32_e32 v49, v51, v146
	v_mul_f32_e32 v49, 0xbfb8aa3b, v49
	v_exp_f32_e32 v49, v49
	v_add_f32_e32 v48, 1.0, v48
	v_rcp_f32_e64 v48, -v48
	v_add_f32_e32 v49, 1.0, v49
	v_rcp_f32_e32 v49, v49
	v_mul_f32_e32 v51, v148, v48
	v_add_f32_e32 v48, v51, v51
	v_exp_f32_e32 v48, v48
	s_nop 0
	v_sub_f32_e32 v48, 1.0, v48
	v_max_f32_e32 v48, 0, v48
	v_cmp_gt_f32_e32 vcc, s17, v48
	v_mul_f32_e32 v50, 0x4f800000, v48
	s_nop 0
	v_cndmask_b32_e32 v48, v48, v50, vcc
	v_sqrt_f32_e32 v50, v48
	s_nop 0
	v_add_u32_e32 v55, -1, v50
	v_fma_f32 v70, -v55, v50, v48
	v_cmp_ge_f32_e64 s[2:3], 0, v70
	v_add_u32_e32 v70, 1, v50
	s_nop 0
	v_cndmask_b32_e64 v55, v50, v55, s[2:3]
	v_fma_f32 v50, -v70, v50, v48
	v_cmp_lt_f32_e64 s[2:3], 0, v50
	s_nop 1
	v_cndmask_b32_e64 v50, v55, v70, s[2:3]
	v_mul_f32_e32 v55, 0x37800000, v50
	v_cndmask_b32_e32 v50, v50, v55, vcc
	v_cmp_class_f32_e32 vcc, v48, v174
	s_nop 1
	v_cndmask_b32_e32 v48, v50, v48, vcc
	v_mul_f32_e32 v48, v49, v48
; __device__ __forceinline__ unsigned cvt_pk_bf16(float lo, float hi) { unsigned r; asm volatile("v_cvt_pk_bf16_f32 %0, %1, %2" : "=v"(r) : "v"(lo), "v"(hi)); return r; }
; __device__ __forceinline__ float bf_lo(unsigned w) { return __uint_as_float(w << 16); }
; __device__ __forceinline__ float bf_hi(unsigned w) { return __uint_as_float(w & 0xffff0000u); }
; __device__ __forceinline__ float sigmoidf_(float x) { return __builtin_amdgcn_rcpf(1.0f + __builtin_amdgcn_exp2f(-x * LOG2E)); }
;     __device__ __forceinline__ void operator()(const f32x4 (&acc)[2][2][4][2], const Unit& u, int wr, int wc, int fr, int fq, const float (&rs)[2][4]) const {
;     ...
;             for (int m = 0; m < 4; ++m) { const int row = row0 + ai * HALF + m * 16;
;                 const u32x4 xw = *(const u32x4*)(XC + (size_t)row * 512 + cbase);
;                 float xc[8] = {bf_lo(xw.x), bf_hi(xw.x), bf_lo(xw.y), bf_hi(xw.y), bf_lo(xw.z), bf_hi(xw.z), bf_lo(xw.w), bf_hi(xw.w)};
;                 float la[8], uu[8];
; #pragma unroll
;                 for (int j = 0; j < 8; ++j) { const float r = sigmoidf_(acc[ai][0][m][j >> 2][j & 3] + ba[j]), ig = sigmoidf_(acc[ai][1][m][j >> 2][j & 3] + bx[j]);
;                     la[j] = -r * sp[j]; const float a2 = __builtin_amdgcn_exp2f(2.0f * la[j]); uu[j] = __builtin_sqrtf(fmaxf(1.0f - a2, 0.0f)) * ig * xc[j]; }
;                 u32x4 w; w.x = cvt_pk_bf16(la[0], la[1]); w.y = cvt_pk_bf16(la[2], la[3]); w.z = cvt_pk_bf16(la[4], la[5]); w.w = cvt_pk_bf16(la[6], la[7]);
;                 *(u32x4*)(LA + (size_t)row * 1024 + dir * 512 + cbase) = w;
;                 w.x = cvt_pk_bf16(uu[0], uu[1]); w.y = cvt_pk_bf16(uu[2], uu[3]); w.z = cvt_pk_bf16(uu[4], uu[5]); w.w = cvt_pk_bf16(uu[6], uu[7]);
;                 *(u32x4*)(U + (size_t)row * 1024 + dir * 512 + cbase) = w; }
	v_mul_f32_e32 v66, v48, v66
	v_cvt_pk_bf16_f32 v48, v56, v57
	v_cvt_pk_bf16_f32 v49, v58, v59
	v_cvt_pk_bf16_f32 v50, v52, v53
	v_lshlrev_b64 v[52:53], 11, v[64:65]
	v_cvt_pk_bf16_f32 v51, v54, v51
	v_lshl_add_u64 v[54:55], s[76:77], 0, v[52:53]
	v_lshl_add_u64 v[54:55], v[54:55], 0, s[64:65]
	v_lshl_add_u64 v[52:53], s[56:57], 0, v[52:53]
	v_lshl_add_u64 v[54:55], v[54:55], 0, v[142:143]
	v_lshl_add_u64 v[52:53], v[52:53], 0, s[64:65]
	global_store_dwordx4 v[54:55], v[48:51], off
	v_lshl_add_u64 v[52:53], v[52:53], 0, v[142:143]
	s_nop 0
	v_cvt_pk_bf16_f32 v48, v60, v61
	v_cvt_pk_bf16_f32 v49, v62, v63
	v_cvt_pk_bf16_f32 v50, v69, v68
	v_cvt_pk_bf16_f32 v51, v67, v66
	global_store_dwordx4 v[52:53], v[48:51], off
	s_nop 1
	v_add_u32_e32 v48, 0x90, v144
	v_ashrrev_i32_e32 v49, 31, v48
	v_lshlrev_b64 v[50:51], 10, v[48:49]
	v_lshl_add_u64 v[50:51], s[4:5], 0, v[50:51]
	v_lshl_add_u64 v[50:51], v[50:51], 0, v[142:143]
	s_nop 0
	v_lshlrev_b32_e32 v58, 16, v224
	v_and_b32_e32 v59, 0xffff0000, v224
	v_lshlrev_b32_e32 v60, 16, v225
	v_and_b32_e32 v54, 0xffff0000, v225
	v_rcp_f32_e32 v55, v40
	v_rcp_f32_e64 v40, -v44
	v_lshlrev_b32_e32 v53, 16, v226
	v_and_b32_e32 v52, 0xffff0000, v226
	v_lshlrev_b32_e32 v51, 16, v227
	v_mul_f32_e32 v40, v183, v40
	v_add_f32_e32 v44, v40, v40
	v_exp_f32_e32 v44, v44
	v_and_b32_e32 v50, 0xffff0000, v227
	v_sub_f32_e32 v44, 1.0, v44
	v_max_f32_e32 v44, 0, v44
	v_cmp_gt_f32_e32 vcc, s17, v44
	v_mul_f32_e32 v56, 0x4f800000, v44
	s_nop 0
	v_cndmask_b32_e32 v44, v44, v56, vcc
	v_sqrt_f32_e32 v56, v44
	s_nop 0
	v_add_u32_e32 v57, -1, v56
	v_fma_f32 v61, -v57, v56, v44
	v_cmp_ge_f32_e64 s[2:3], 0, v61
	v_add_u32_e32 v61, 1, v56
	s_nop 0
	v_cndmask_b32_e64 v57, v56, v57, s[2:3]
	v_fma_f32 v56, -v61, v56, v44
	v_cmp_lt_f32_e64 s[2:3], 0, v56
	s_nop 1
	v_cndmask_b32_e64 v56, v57, v61, s[2:3]
	v_mul_f32_e32 v57, 0x37800000, v56
	v_cndmask_b32_e32 v56, v56, v57, vcc
	v_cmp_class_f32_e32 vcc, v44, v174
	s_nop 1
	v_cndmask_b32_e32 v44, v56, v44, vcc
	v_mul_f32_e32 v44, v55, v44
	v_rcp_f32_e32 v55, v41
	v_rcp_f32_e64 v41, -v45
	v_mul_f32_e32 v44, v44, v58
	v_mul_f32_e32 v41, v182, v41
	v_add_f32_e32 v45, v41, v41
	v_exp_f32_e32 v45, v45
	s_nop 0
	v_sub_f32_e32 v45, 1.0, v45
	v_max_f32_e32 v45, 0, v45
	v_cmp_gt_f32_e32 vcc, s17, v45
	v_mul_f32_e32 v56, 0x4f800000, v45
	s_nop 0
	v_cndmask_b32_e32 v45, v45, v56, vcc
	v_sqrt_f32_e32 v56, v45
	s_nop 0
	v_add_u32_e32 v57, -1, v56
	v_fma_f32 v58, -v57, v56, v45
	v_cmp_ge_f32_e64 s[2:3], 0, v58
	v_add_u32_e32 v58, 1, v56
	s_nop 0
	v_cndmask_b32_e64 v57, v56, v57, s[2:3]
	v_fma_f32 v56, -v58, v56, v45
	v_cmp_lt_f32_e64 s[2:3], 0, v56
	s_nop 1
	v_cndmask_b32_e64 v56, v57, v58, s[2:3]
	v_mul_f32_e32 v57, 0x37800000, v56
	v_cndmask_b32_e32 v56, v56, v57, vcc
	v_cmp_class_f32_e32 vcc, v45, v174
	s_nop 1
	v_cndmask_b32_e32 v45, v56, v45, vcc
	v_mul_f32_e32 v45, v55, v45
	v_rcp_f32_e32 v55, v42
	v_rcp_f32_e64 v42, -v46
	v_mul_f32_e32 v45, v45, v59
	v_mul_f32_e32 v42, v181, v42
	v_add_f32_e32 v46, v42, v42
	v_exp_f32_e32 v46, v46
	s_nop 0
	v_sub_f32_e32 v46, 1.0, v46
	v_max_f32_e32 v46, 0, v46
	v_cmp_gt_f32_e32 vcc, s17, v46
	v_mul_f32_e32 v56, 0x4f800000, v46
	s_nop 0
	v_cndmask_b32_e32 v46, v46, v56, vcc
	v_sqrt_f32_e32 v56, v46
	s_nop 0
	v_add_u32_e32 v57, -1, v56
	v_fma_f32 v58, -v57, v56, v46
	v_cmp_ge_f32_e64 s[2:3], 0, v58
	v_add_u32_e32 v58, 1, v56
	s_nop 0
	v_cndmask_b32_e64 v57, v56, v57, s[2:3]
	v_fma_f32 v56, -v58, v56, v46
	v_cmp_lt_f32_e64 s[2:3], 0, v56
	s_nop 1
	v_cndmask_b32_e64 v56, v57, v58, s[2:3]
	v_mul_f32_e32 v57, 0x37800000, v56
	v_cndmask_b32_e32 v56, v56, v57, vcc
	v_cmp_class_f32_e32 vcc, v46, v174
	s_nop 1
	v_cndmask_b32_e32 v46, v56, v46, vcc
	v_mul_f32_e32 v46, v55, v46
	v_rcp_f32_e32 v55, v43
	v_rcp_f32_e64 v43, -v47
	v_mul_f32_e32 v46, v46, v60
	v_mul_f32_e32 v43, v172, v43
	v_add_f32_e32 v47, v43, v43
	v_exp_f32_e32 v47, v47
	s_nop 0
	v_sub_f32_e32 v47, 1.0, v47
	v_max_f32_e32 v47, 0, v47
	v_cmp_gt_f32_e32 vcc, s17, v47
	v_mul_f32_e32 v56, 0x4f800000, v47
	s_nop 0
	v_cndmask_b32_e32 v47, v47, v56, vcc
	v_sqrt_f32_e32 v56, v47
	s_nop 0
	v_add_u32_e32 v57, -1, v56
	v_fma_f32 v58, -v57, v56, v47
	v_cmp_ge_f32_e64 s[2:3], 0, v58
	v_add_u32_e32 v58, 1, v56
	s_nop 0
	v_cndmask_b32_e64 v57, v56, v57, s[2:3]
	v_fma_f32 v56, -v58, v56, v47
	v_cmp_lt_f32_e64 s[2:3], 0, v56
	s_nop 1
	v_cndmask_b32_e64 v56, v57, v58, s[2:3]
	v_mul_f32_e32 v57, 0x37800000, v56
	v_cndmask_b32_e32 v56, v56, v57, vcc
	v_cmp_class_f32_e32 vcc, v47, v174
	s_nop 1
	v_cndmask_b32_e32 v47, v56, v47, vcc
	v_mul_f32_e32 v47, v55, v47
	v_mul_f32_e32 v47, v47, v54
	v_add_f32_e32 v54, v36, v36
	v_exp_f32_e32 v54, v54
	s_nop 0
	v_sub_f32_e32 v54, 1.0, v54
	v_max_f32_e32 v54, 0, v54
	v_cmp_gt_f32_e32 vcc, s17, v54
	v_mul_f32_e32 v55, 0x4f800000, v54
	s_nop 0
	v_cndmask_b32_e32 v54, v54, v55, vcc
	v_sqrt_f32_e32 v55, v54
	s_nop 0
	v_add_u32_e32 v56, -1, v55
	v_fma_f32 v57, -v56, v55, v54
	v_cmp_ge_f32_e64 s[2:3], 0, v57
	v_add_u32_e32 v57, 1, v55
	s_nop 0
	v_cndmask_b32_e64 v56, v55, v56, s[2:3]
	v_fma_f32 v55, -v57, v55, v54
	v_cmp_lt_f32_e64 s[2:3], 0, v55
	s_nop 1
	v_cndmask_b32_e64 v55, v56, v57, s[2:3]
	v_mul_f32_e32 v56, 0x37800000, v55
	v_cndmask_b32_e32 v55, v55, v56, vcc
	v_cmp_class_f32_e32 vcc, v54, v174
	s_nop 1
	v_cndmask_b32_e32 v54, v55, v54, vcc
	v_mul_f32_e32 v32, v32, v54
	v_mul_f32_e32 v53, v32, v53
	v_add_f32_e32 v32, v37, v157
	v_mul_f32_e32 v32, 0xbfb8aa3b, v32
	v_exp_f32_e32 v32, v32
	s_nop 0
	v_add_f32_e32 v32, 1.0, v32
	v_rcp_f32_e64 v32, -v32
	s_nop 0
	v_mul_f32_e32 v37, v160, v32
	v_add_f32_e32 v32, v37, v37
	v_exp_f32_e32 v32, v32
	s_nop 0
	v_sub_f32_e32 v32, 1.0, v32
; __device__ __forceinline__ unsigned cvt_pk_bf16(float lo, float hi) { unsigned r; asm volatile("v_cvt_pk_bf16_f32 %0, %1, %2" : "=v"(r) : "v"(lo), "v"(hi)); return r; }
; __device__ __forceinline__ float sigmoidf_(float x) { return __builtin_amdgcn_rcpf(1.0f + __builtin_amdgcn_exp2f(-x * LOG2E)); }
;     __device__ __forceinline__ void operator()(const f32x4 (&acc)[2][2][4][2], const Unit& u, int wr, int wc, int fr, int fq, const float (&rs)[2][4]) const {
;     ...
;                 for (int j = 0; j < 8; ++j) { const float r = sigmoidf_(acc[ai][0][m][j >> 2][j & 3] + ba[j]), ig = sigmoidf_(acc[ai][1][m][j >> 2][j & 3] + bx[j]);
;                     la[j] = -r * sp[j]; const float a2 = __builtin_amdgcn_exp2f(2.0f * la[j]); uu[j] = __builtin_sqrtf(fmaxf(1.0f - a2, 0.0f)) * ig * xc[j]; }
;                 u32x4 w; w.x = cvt_pk_bf16(la[0], la[1]); w.y = cvt_pk_bf16(la[2], la[3]); w.z = cvt_pk_bf16(la[4], la[5]); w.w = cvt_pk_bf16(la[6], la[7]);
;                 *(u32x4*)(LA + (size_t)row * 1024 + dir * 512 + cbase) = w;
;                 w.x = cvt_pk_bf16(uu[0], uu[1]); w.y = cvt_pk_bf16(uu[2], uu[3]); w.z = cvt_pk_bf16(uu[4], uu[5]); w.w = cvt_pk_bf16(uu[6], uu[7]);
;                 *(u32x4*)(U + (size_t)row * 1024 + dir * 512 + cbase) = w; }
	v_max_f32_e32 v32, 0, v32
	v_cmp_gt_f32_e32 vcc, s17, v32
	v_mul_f32_e32 v54, 0x4f800000, v32
	s_nop 0
	v_cndmask_b32_e32 v32, v32, v54, vcc
	v_sqrt_f32_e32 v54, v32
	s_nop 0
	v_add_u32_e32 v55, -1, v54
	v_fma_f32 v56, -v55, v54, v32
	v_cmp_ge_f32_e64 s[2:3], 0, v56
	v_add_u32_e32 v56, 1, v54
	s_nop 0
	v_cndmask_b32_e64 v55, v54, v55, s[2:3]
	v_fma_f32 v54, -v56, v54, v32
	v_cmp_lt_f32_e64 s[2:3], 0, v54
	s_nop 1
	v_cndmask_b32_e64 v54, v55, v56, s[2:3]
	v_mul_f32_e32 v55, 0x37800000, v54
	v_cndmask_b32_e32 v54, v54, v55, vcc
	v_cmp_class_f32_e32 vcc, v32, v174
	s_nop 1
	v_cndmask_b32_e32 v32, v54, v32, vcc
	v_mul_f32_e32 v32, v33, v32
	v_mul_f32_e32 v52, v32, v52
	v_add_f32_e32 v32, v38, v155
	v_mul_f32_e32 v32, 0xbfb8aa3b, v32
	v_exp_f32_e32 v32, v32
	v_add_f32_e32 v33, v34, v154
	v_mul_f32_e32 v33, 0xbfb8aa3b, v33
	v_exp_f32_e32 v33, v33
	v_add_f32_e32 v32, 1.0, v32
	v_rcp_f32_e64 v32, -v32
	v_add_f32_e32 v33, 1.0, v33
	v_rcp_f32_e32 v33, v33
	v_mul_f32_e32 v38, v149, v32
	v_add_f32_e32 v32, v38, v38
	v_exp_f32_e32 v32, v32
	s_nop 0
	v_sub_f32_e32 v32, 1.0, v32
	v_max_f32_e32 v32, 0, v32
	v_cmp_gt_f32_e32 vcc, s17, v32
	v_mul_f32_e32 v34, 0x4f800000, v32
	s_nop 0
	v_cndmask_b32_e32 v32, v32, v34, vcc
	v_sqrt_f32_e32 v34, v32
	s_nop 0
	v_add_u32_e32 v54, -1, v34
	v_fma_f32 v55, -v54, v34, v32
	v_cmp_ge_f32_e64 s[2:3], 0, v55
	v_add_u32_e32 v55, 1, v34
	s_nop 0
	v_cndmask_b32_e64 v54, v34, v54, s[2:3]
	v_fma_f32 v34, -v55, v34, v32
	v_cmp_lt_f32_e64 s[2:3], 0, v34
	s_nop 1
	v_cndmask_b32_e64 v34, v54, v55, s[2:3]
	v_mul_f32_e32 v54, 0x37800000, v34
	v_cndmask_b32_e32 v34, v34, v54, vcc
	v_cmp_class_f32_e32 vcc, v32, v174
	s_nop 1
	v_cndmask_b32_e32 v32, v34, v32, vcc
	v_mul_f32_e32 v32, v33, v32
	v_mul_f32_e32 v51, v32, v51
	v_add_f32_e32 v32, v39, v147
	v_mul_f32_e32 v32, 0xbfb8aa3b, v32
	v_exp_f32_e32 v32, v32
	v_add_f32_e32 v33, v35, v146
	v_mul_f32_e32 v33, 0xbfb8aa3b, v33
	v_exp_f32_e32 v33, v33
	v_add_f32_e32 v32, 1.0, v32
	v_rcp_f32_e64 v32, -v32
	v_add_f32_e32 v33, 1.0, v33
	v_rcp_f32_e32 v33, v33
	v_mul_f32_e32 v35, v148, v32
	v_add_f32_e32 v32, v35, v35
	v_exp_f32_e32 v32, v32
	s_nop 0
	v_sub_f32_e32 v32, 1.0, v32
	v_max_f32_e32 v32, 0, v32
	v_cmp_gt_f32_e32 vcc, s17, v32
	v_mul_f32_e32 v34, 0x4f800000, v32
	s_nop 0
	v_cndmask_b32_e32 v32, v32, v34, vcc
	v_sqrt_f32_e32 v34, v32
	s_nop 0
	v_add_u32_e32 v39, -1, v34
	v_fma_f32 v54, -v39, v34, v32
	v_cmp_ge_f32_e64 s[2:3], 0, v54
	v_add_u32_e32 v54, 1, v34
	s_nop 0
	v_cndmask_b32_e64 v39, v34, v39, s[2:3]
	v_fma_f32 v34, -v54, v34, v32
	v_cmp_lt_f32_e64 s[2:3], 0, v34
	s_nop 1
	v_cndmask_b32_e64 v34, v39, v54, s[2:3]
	v_mul_f32_e32 v39, 0x37800000, v34
	v_cndmask_b32_e32 v34, v34, v39, vcc
	v_cmp_class_f32_e32 vcc, v32, v174
	s_nop 1
	v_cndmask_b32_e32 v32, v34, v32, vcc
	v_mul_f32_e32 v32, v33, v32
	v_mul_f32_e32 v50, v32, v50
	v_cvt_pk_bf16_f32 v32, v40, v41
	v_cvt_pk_bf16_f32 v33, v42, v43
	v_cvt_pk_bf16_f32 v34, v36, v37
	v_lshlrev_b64 v[36:37], 11, v[48:49]
	v_cvt_pk_bf16_f32 v35, v38, v35
	v_lshl_add_u64 v[38:39], s[76:77], 0, v[36:37]
	v_lshl_add_u64 v[38:39], v[38:39], 0, s[64:65]
	v_lshl_add_u64 v[36:37], s[56:57], 0, v[36:37]
	v_lshl_add_u64 v[38:39], v[38:39], 0, v[142:143]
	v_lshl_add_u64 v[36:37], v[36:37], 0, s[64:65]
	global_store_dwordx4 v[38:39], v[32:35], off
	v_lshl_add_u64 v[36:37], v[36:37], 0, v[142:143]
	s_nop 0
	v_cvt_pk_bf16_f32 v32, v44, v45
	v_cvt_pk_bf16_f32 v33, v46, v47
	v_cvt_pk_bf16_f32 v34, v53, v52
	v_cvt_pk_bf16_f32 v35, v51, v50
	global_store_dwordx4 v[36:37], v[32:35], off
	s_nop 1
	v_add_u32_e32 v32, 0xa0, v144
	v_ashrrev_i32_e32 v33, 31, v32
	v_lshlrev_b64 v[34:35], 10, v[32:33]
	v_lshl_add_u64 v[34:35], s[4:5], 0, v[34:35]
	v_lshl_add_u64 v[34:35], v[34:35], 0, v[142:143]
	s_nop 0
	v_lshlrev_b32_e32 v42, 16, v228
	v_and_b32_e32 v43, 0xffff0000, v228
	v_lshlrev_b32_e32 v44, 16, v229
	v_and_b32_e32 v38, 0xffff0000, v229
	v_rcp_f32_e32 v39, v24
	v_rcp_f32_e64 v24, -v28
	v_lshlrev_b32_e32 v37, 16, v230
	v_and_b32_e32 v36, 0xffff0000, v230
	v_lshlrev_b32_e32 v35, 16, v231
	v_mul_f32_e32 v24, v183, v24
	v_add_f32_e32 v28, v24, v24
	v_exp_f32_e32 v28, v28
	v_and_b32_e32 v34, 0xffff0000, v231
	v_sub_f32_e32 v28, 1.0, v28
	v_max_f32_e32 v28, 0, v28
	v_cmp_gt_f32_e32 vcc, s17, v28
	v_mul_f32_e32 v40, 0x4f800000, v28
	s_nop 0
	v_cndmask_b32_e32 v28, v28, v40, vcc
	v_sqrt_f32_e32 v40, v28
	s_nop 0
	v_add_u32_e32 v41, -1, v40
	v_fma_f32 v45, -v41, v40, v28
	v_cmp_ge_f32_e64 s[2:3], 0, v45
	v_add_u32_e32 v45, 1, v40
	s_nop 0
	v_cndmask_b32_e64 v41, v40, v41, s[2:3]
	v_fma_f32 v40, -v45, v40, v28
	v_cmp_lt_f32_e64 s[2:3], 0, v40
	s_nop 1
	v_cndmask_b32_e64 v40, v41, v45, s[2:3]
	v_mul_f32_e32 v41, 0x37800000, v40
	v_cndmask_b32_e32 v40, v40, v41, vcc
	v_cmp_class_f32_e32 vcc, v28, v174
	s_nop 1
	v_cndmask_b32_e32 v28, v40, v28, vcc
	v_mul_f32_e32 v28, v39, v28
	v_rcp_f32_e32 v39, v25
	v_rcp_f32_e64 v25, -v29
	v_mul_f32_e32 v28, v28, v42
	v_mul_f32_e32 v25, v182, v25
	v_add_f32_e32 v29, v25, v25
	v_exp_f32_e32 v29, v29
	s_nop 0
	v_sub_f32_e32 v29, 1.0, v29
	v_max_f32_e32 v29, 0, v29
	v_cmp_gt_f32_e32 vcc, s17, v29
	v_mul_f32_e32 v40, 0x4f800000, v29
	s_nop 0
	v_cndmask_b32_e32 v29, v29, v40, vcc
	v_sqrt_f32_e32 v40, v29
	s_nop 0
	v_add_u32_e32 v41, -1, v40
	v_fma_f32 v42, -v41, v40, v29
	v_cmp_ge_f32_e64 s[2:3], 0, v42
	v_add_u32_e32 v42, 1, v40
	s_nop 0
	v_cndmask_b32_e64 v41, v40, v41, s[2:3]
	v_fma_f32 v40, -v42, v40, v29
	v_cmp_lt_f32_e64 s[2:3], 0, v40
	s_nop 1
	v_cndmask_b32_e64 v40, v41, v42, s[2:3]
	v_mul_f32_e32 v41, 0x37800000, v40
	v_cndmask_b32_e32 v40, v40, v41, vcc
	v_cmp_class_f32_e32 vcc, v29, v174
	s_nop 1
	v_cndmask_b32_e32 v29, v40, v29, vcc
; __device__ __forceinline__ float sigmoidf_(float x) { return __builtin_amdgcn_rcpf(1.0f + __builtin_amdgcn_exp2f(-x * LOG2E)); }
;     __device__ __forceinline__ void operator()(const f32x4 (&acc)[2][2][4][2], const Unit& u, int wr, int wc, int fr, int fq, const float (&rs)[2][4]) const {
;     ...
;                 for (int j = 0; j < 8; ++j) { const float r = sigmoidf_(acc[ai][0][m][j >> 2][j & 3] + ba[j]), ig = sigmoidf_(acc[ai][1][m][j >> 2][j & 3] + bx[j]);
;                     la[j] = -r * sp[j]; const float a2 = __builtin_amdgcn_exp2f(2.0f * la[j]); uu[j] = __builtin_sqrtf(fmaxf(1.0f - a2, 0.0f)) * ig * xc[j]; }
	v_mul_f32_e32 v29, v39, v29
	v_rcp_f32_e32 v39, v26
	v_rcp_f32_e64 v26, -v30
	v_mul_f32_e32 v29, v29, v43
	v_mul_f32_e32 v26, v181, v26
	v_add_f32_e32 v30, v26, v26
	v_exp_f32_e32 v30, v30
	s_nop 0
	v_sub_f32_e32 v30, 1.0, v30
	v_max_f32_e32 v30, 0, v30
	v_cmp_gt_f32_e32 vcc, s17, v30
	v_mul_f32_e32 v40, 0x4f800000, v30
	s_nop 0
	v_cndmask_b32_e32 v30, v30, v40, vcc
	v_sqrt_f32_e32 v40, v30
	s_nop 0
	v_add_u32_e32 v41, -1, v40
	v_fma_f32 v42, -v41, v40, v30
	v_cmp_ge_f32_e64 s[2:3], 0, v42
	v_add_u32_e32 v42, 1, v40
	s_nop 0
	v_cndmask_b32_e64 v41, v40, v41, s[2:3]
	v_fma_f32 v40, -v42, v40, v30
	v_cmp_lt_f32_e64 s[2:3], 0, v40
	s_nop 1
	v_cndmask_b32_e64 v40, v41, v42, s[2:3]
	v_mul_f32_e32 v41, 0x37800000, v40
	v_cndmask_b32_e32 v40, v40, v41, vcc
	v_cmp_class_f32_e32 vcc, v30, v174
	s_nop 1
	v_cndmask_b32_e32 v30, v40, v30, vcc
	v_mul_f32_e32 v30, v39, v30
	v_rcp_f32_e32 v39, v27
	v_rcp_f32_e64 v27, -v31
	v_mul_f32_e32 v30, v30, v44
	v_mul_f32_e32 v27, v172, v27
	v_add_f32_e32 v31, v27, v27
	v_exp_f32_e32 v31, v31
	s_nop 0
	v_sub_f32_e32 v31, 1.0, v31
	v_max_f32_e32 v31, 0, v31
	v_cmp_gt_f32_e32 vcc, s17, v31
	v_mul_f32_e32 v40, 0x4f800000, v31
	s_nop 0
	v_cndmask_b32_e32 v31, v31, v40, vcc
	v_sqrt_f32_e32 v40, v31
	s_nop 0
	v_add_u32_e32 v41, -1, v40
	v_fma_f32 v42, -v41, v40, v31
	v_cmp_ge_f32_e64 s[2:3], 0, v42
	v_add_u32_e32 v42, 1, v40
	s_nop 0
	v_cndmask_b32_e64 v41, v40, v41, s[2:3]
	v_fma_f32 v40, -v42, v40, v31
	v_cmp_lt_f32_e64 s[2:3], 0, v40
	s_nop 1
	v_cndmask_b32_e64 v40, v41, v42, s[2:3]
	v_mul_f32_e32 v41, 0x37800000, v40
	v_cndmask_b32_e32 v40, v40, v41, vcc
	v_cmp_class_f32_e32 vcc, v31, v174
	s_nop 1
	v_cndmask_b32_e32 v31, v40, v31, vcc
	v_mul_f32_e32 v31, v39, v31
	v_mul_f32_e32 v31, v31, v38
	v_add_f32_e32 v38, v20, v20
	v_exp_f32_e32 v38, v38
	s_nop 0
	v_sub_f32_e32 v38, 1.0, v38
	v_max_f32_e32 v38, 0, v38
	v_cmp_gt_f32_e32 vcc, s17, v38
	v_mul_f32_e32 v39, 0x4f800000, v38
	s_nop 0
	v_cndmask_b32_e32 v38, v38, v39, vcc
	v_sqrt_f32_e32 v39, v38
	s_nop 0
	v_add_u32_e32 v40, -1, v39
	v_fma_f32 v41, -v40, v39, v38
	v_cmp_ge_f32_e64 s[2:3], 0, v41
	v_add_u32_e32 v41, 1, v39
	s_nop 0
	v_cndmask_b32_e64 v40, v39, v40, s[2:3]
	v_fma_f32 v39, -v41, v39, v38
	v_cmp_lt_f32_e64 s[2:3], 0, v39
	s_nop 1
	v_cndmask_b32_e64 v39, v40, v41, s[2:3]
	v_mul_f32_e32 v40, 0x37800000, v39
	v_cndmask_b32_e32 v39, v39, v40, vcc
	v_cmp_class_f32_e32 vcc, v38, v174
	s_nop 1
	v_cndmask_b32_e32 v38, v39, v38, vcc
	v_mul_f32_e32 v16, v16, v38
	v_mul_f32_e32 v37, v16, v37
	v_add_f32_e32 v16, v21, v157
	v_mul_f32_e32 v16, 0xbfb8aa3b, v16
	v_exp_f32_e32 v16, v16
	s_nop 0
	v_add_f32_e32 v16, 1.0, v16
	v_rcp_f32_e64 v16, -v16
	s_nop 0
	v_mul_f32_e32 v21, v160, v16
	v_add_f32_e32 v16, v21, v21
	v_exp_f32_e32 v16, v16
	s_nop 0
	v_sub_f32_e32 v16, 1.0, v16
	v_max_f32_e32 v16, 0, v16
	v_cmp_gt_f32_e32 vcc, s17, v16
	v_mul_f32_e32 v38, 0x4f800000, v16
	s_nop 0
	v_cndmask_b32_e32 v16, v16, v38, vcc
	v_sqrt_f32_e32 v38, v16
	s_nop 0
	v_add_u32_e32 v39, -1, v38
	v_fma_f32 v40, -v39, v38, v16
	v_cmp_ge_f32_e64 s[2:3], 0, v40
	v_add_u32_e32 v40, 1, v38
	s_nop 0
	v_cndmask_b32_e64 v39, v38, v39, s[2:3]
	v_fma_f32 v38, -v40, v38, v16
	v_cmp_lt_f32_e64 s[2:3], 0, v38
	s_nop 1
	v_cndmask_b32_e64 v38, v39, v40, s[2:3]
	v_mul_f32_e32 v39, 0x37800000, v38
	v_cndmask_b32_e32 v38, v38, v39, vcc
	v_cmp_class_f32_e32 vcc, v16, v174
	s_nop 1
	v_cndmask_b32_e32 v16, v38, v16, vcc
	v_mul_f32_e32 v16, v17, v16
	v_mul_f32_e32 v36, v16, v36
	v_add_f32_e32 v16, v22, v155
	v_mul_f32_e32 v16, 0xbfb8aa3b, v16
	v_exp_f32_e32 v16, v16
	v_add_f32_e32 v17, v18, v154
	v_mul_f32_e32 v17, 0xbfb8aa3b, v17
	v_exp_f32_e32 v17, v17
	v_add_f32_e32 v16, 1.0, v16
	v_rcp_f32_e64 v16, -v16
	v_add_f32_e32 v17, 1.0, v17
	v_rcp_f32_e32 v17, v17
	v_mul_f32_e32 v22, v149, v16
	v_add_f32_e32 v16, v22, v22
	v_exp_f32_e32 v16, v16
	s_nop 0
	v_sub_f32_e32 v16, 1.0, v16
	v_max_f32_e32 v16, 0, v16
	v_cmp_gt_f32_e32 vcc, s17, v16
	v_mul_f32_e32 v18, 0x4f800000, v16
	s_nop 0
	v_cndmask_b32_e32 v16, v16, v18, vcc
	v_sqrt_f32_e32 v18, v16
	s_nop 0
	v_add_u32_e32 v38, -1, v18
	v_fma_f32 v39, -v38, v18, v16
	v_cmp_ge_f32_e64 s[2:3], 0, v39
	v_add_u32_e32 v39, 1, v18
	s_nop 0
	v_cndmask_b32_e64 v38, v18, v38, s[2:3]
	v_fma_f32 v18, -v39, v18, v16
	v_cmp_lt_f32_e64 s[2:3], 0, v18
	s_nop 1
	v_cndmask_b32_e64 v18, v38, v39, s[2:3]
	v_mul_f32_e32 v38, 0x37800000, v18
	v_cndmask_b32_e32 v18, v18, v38, vcc
	v_cmp_class_f32_e32 vcc, v16, v174
	s_nop 1
	v_cndmask_b32_e32 v16, v18, v16, vcc
	v_mul_f32_e32 v16, v17, v16
	v_mul_f32_e32 v35, v16, v35
	v_add_f32_e32 v16, v23, v147
	v_mul_f32_e32 v16, 0xbfb8aa3b, v16
	v_exp_f32_e32 v16, v16
	v_add_f32_e32 v17, v19, v146
	v_mul_f32_e32 v17, 0xbfb8aa3b, v17
	v_exp_f32_e32 v17, v17
	v_add_f32_e32 v16, 1.0, v16
	v_rcp_f32_e64 v16, -v16
	v_add_f32_e32 v17, 1.0, v17
	v_rcp_f32_e32 v17, v17
	v_mul_f32_e32 v19, v148, v16
	v_add_f32_e32 v16, v19, v19
	v_exp_f32_e32 v16, v16
	s_nop 0
	v_sub_f32_e32 v16, 1.0, v16
	v_max_f32_e32 v16, 0, v16
	v_cmp_gt_f32_e32 vcc, s17, v16
	v_mul_f32_e32 v18, 0x4f800000, v16
	s_nop 0
	v_cndmask_b32_e32 v16, v16, v18, vcc
	v_sqrt_f32_e32 v18, v16
	s_nop 0
	v_add_u32_e32 v23, -1, v18
	v_fma_f32 v38, -v23, v18, v16
	v_cmp_ge_f32_e64 s[2:3], 0, v38
	v_add_u32_e32 v38, 1, v18
	s_nop 0
	v_cndmask_b32_e64 v23, v18, v23, s[2:3]
	v_fma_f32 v18, -v38, v18, v16
	v_cmp_lt_f32_e64 s[2:3], 0, v18
	s_nop 1
	v_cndmask_b32_e64 v18, v23, v38, s[2:3]
	v_mul_f32_e32 v23, 0x37800000, v18
	v_cndmask_b32_e32 v18, v18, v23, vcc
	v_cmp_class_f32_e32 vcc, v16, v174
	s_nop 1
	v_cndmask_b32_e32 v16, v18, v16, vcc
	v_mul_f32_e32 v16, v17, v16
	v_mul_f32_e32 v34, v16, v34
; __device__ __forceinline__ unsigned cvt_pk_bf16(float lo, float hi) { unsigned r; asm volatile("v_cvt_pk_bf16_f32 %0, %1, %2" : "=v"(r) : "v"(lo), "v"(hi)); return r; }
; __device__ __forceinline__ float bf_lo(unsigned w) { return __uint_as_float(w << 16); }
; __device__ __forceinline__ float bf_hi(unsigned w) { return __uint_as_float(w & 0xffff0000u); }
; __device__ __forceinline__ float sigmoidf_(float x) { return __builtin_amdgcn_rcpf(1.0f + __builtin_amdgcn_exp2f(-x * LOG2E)); }
;     __device__ __forceinline__ void operator()(const f32x4 (&acc)[2][2][4][2], const Unit& u, int wr, int wc, int fr, int fq, const float (&rs)[2][4]) const {
;     ...
;             for (int m = 0; m < 4; ++m) { const int row = row0 + ai * HALF + m * 16;
;                 const u32x4 xw = *(const u32x4*)(XC + (size_t)row * 512 + cbase);
;                 float xc[8] = {bf_lo(xw.x), bf_hi(xw.x), bf_lo(xw.y), bf_hi(xw.y), bf_lo(xw.z), bf_hi(xw.z), bf_lo(xw.w), bf_hi(xw.w)};
;                 float la[8], uu[8];
; #pragma unroll
;                 for (int j = 0; j < 8; ++j) { const float r = sigmoidf_(acc[ai][0][m][j >> 2][j & 3] + ba[j]), ig = sigmoidf_(acc[ai][1][m][j >> 2][j & 3] + bx[j]);
;                     la[j] = -r * sp[j]; const float a2 = __builtin_amdgcn_exp2f(2.0f * la[j]); uu[j] = __builtin_sqrtf(fmaxf(1.0f - a2, 0.0f)) * ig * xc[j]; }
;                 u32x4 w; w.x = cvt_pk_bf16(la[0], la[1]); w.y = cvt_pk_bf16(la[2], la[3]); w.z = cvt_pk_bf16(la[4], la[5]); w.w = cvt_pk_bf16(la[6], la[7]);
;                 *(u32x4*)(LA + (size_t)row * 1024 + dir * 512 + cbase) = w;
;                 w.x = cvt_pk_bf16(uu[0], uu[1]); w.y = cvt_pk_bf16(uu[2], uu[3]); w.z = cvt_pk_bf16(uu[4], uu[5]); w.w = cvt_pk_bf16(uu[6], uu[7]);
;                 *(u32x4*)(U + (size_t)row * 1024 + dir * 512 + cbase) = w; }
	v_cvt_pk_bf16_f32 v16, v24, v25
	v_cvt_pk_bf16_f32 v17, v26, v27
	v_cvt_pk_bf16_f32 v18, v20, v21
	v_lshlrev_b64 v[20:21], 11, v[32:33]
	v_cvt_pk_bf16_f32 v19, v22, v19
	v_lshl_add_u64 v[22:23], s[76:77], 0, v[20:21]
	v_lshl_add_u64 v[22:23], v[22:23], 0, s[64:65]
	v_lshl_add_u64 v[20:21], s[56:57], 0, v[20:21]
	v_lshl_add_u64 v[22:23], v[22:23], 0, v[142:143]
	v_lshl_add_u64 v[20:21], v[20:21], 0, s[64:65]
	global_store_dwordx4 v[22:23], v[16:19], off
	v_lshl_add_u64 v[20:21], v[20:21], 0, v[142:143]
	s_nop 0
	v_cvt_pk_bf16_f32 v16, v28, v29
	v_cvt_pk_bf16_f32 v17, v30, v31
	v_cvt_pk_bf16_f32 v18, v37, v36
	v_cvt_pk_bf16_f32 v19, v35, v34
	global_store_dwordx4 v[20:21], v[16:19], off
	s_nop 1
	v_add_u32_e32 v16, 0xb0, v144
	v_ashrrev_i32_e32 v17, 31, v16
	v_lshlrev_b64 v[18:19], 10, v[16:17]
	v_lshl_add_u64 v[18:19], s[4:5], 0, v[18:19]
	v_lshl_add_u64 v[18:19], v[18:19], 0, v[142:143]
	s_nop 0
	v_lshlrev_b32_e32 v26, 16, v232
	v_and_b32_e32 v27, 0xffff0000, v232
	v_lshlrev_b32_e32 v28, 16, v233
	v_and_b32_e32 v22, 0xffff0000, v233
	v_rcp_f32_e32 v23, v8
	v_rcp_f32_e64 v8, -v12
	v_lshlrev_b32_e32 v21, 16, v234
	v_and_b32_e32 v20, 0xffff0000, v234
	v_lshlrev_b32_e32 v19, 16, v235
	v_mul_f32_e32 v8, v183, v8
	v_add_f32_e32 v12, v8, v8
	v_exp_f32_e32 v12, v12
	v_and_b32_e32 v18, 0xffff0000, v235
	v_sub_f32_e32 v12, 1.0, v12
	v_max_f32_e32 v12, 0, v12
	v_cmp_gt_f32_e32 vcc, s17, v12
	v_mul_f32_e32 v24, 0x4f800000, v12
	s_nop 0
	v_cndmask_b32_e32 v12, v12, v24, vcc
	v_sqrt_f32_e32 v24, v12
	s_nop 0
	v_add_u32_e32 v25, -1, v24
	v_fma_f32 v29, -v25, v24, v12
	v_cmp_ge_f32_e64 s[2:3], 0, v29
	v_add_u32_e32 v29, 1, v24
	s_nop 0
	v_cndmask_b32_e64 v25, v24, v25, s[2:3]
	v_fma_f32 v24, -v29, v24, v12
	v_cmp_lt_f32_e64 s[2:3], 0, v24
	s_nop 1
	v_cndmask_b32_e64 v24, v25, v29, s[2:3]
	v_mul_f32_e32 v25, 0x37800000, v24
	v_cndmask_b32_e32 v24, v24, v25, vcc
	v_cmp_class_f32_e32 vcc, v12, v174
	s_nop 1
	v_cndmask_b32_e32 v12, v24, v12, vcc
	v_mul_f32_e32 v12, v23, v12
	v_rcp_f32_e32 v23, v9
	v_rcp_f32_e64 v9, -v13
	v_mul_f32_e32 v12, v12, v26
	v_mul_f32_e32 v9, v182, v9
	v_add_f32_e32 v13, v9, v9
	v_exp_f32_e32 v13, v13
	s_nop 0
	v_sub_f32_e32 v13, 1.0, v13
	v_max_f32_e32 v13, 0, v13
	v_cmp_gt_f32_e32 vcc, s17, v13
	v_mul_f32_e32 v24, 0x4f800000, v13
	s_nop 0
	v_cndmask_b32_e32 v13, v13, v24, vcc
	v_sqrt_f32_e32 v24, v13
	s_nop 0
	v_add_u32_e32 v25, -1, v24
	v_fma_f32 v26, -v25, v24, v13
	v_cmp_ge_f32_e64 s[2:3], 0, v26
	v_add_u32_e32 v26, 1, v24
	s_nop 0
	v_cndmask_b32_e64 v25, v24, v25, s[2:3]
	v_fma_f32 v24, -v26, v24, v13
	v_cmp_lt_f32_e64 s[2:3], 0, v24
	s_nop 1
	v_cndmask_b32_e64 v24, v25, v26, s[2:3]
	v_mul_f32_e32 v25, 0x37800000, v24
	v_cndmask_b32_e32 v24, v24, v25, vcc
	v_cmp_class_f32_e32 vcc, v13, v174
	s_nop 1
	v_cndmask_b32_e32 v13, v24, v13, vcc
	v_mul_f32_e32 v13, v23, v13
	v_rcp_f32_e32 v23, v10
	v_rcp_f32_e64 v10, -v14
	v_mul_f32_e32 v13, v13, v27
	v_mul_f32_e32 v10, v181, v10
	v_add_f32_e32 v14, v10, v10
	v_exp_f32_e32 v14, v14
	s_nop 0
	v_sub_f32_e32 v14, 1.0, v14
	v_max_f32_e32 v14, 0, v14
	v_cmp_gt_f32_e32 vcc, s17, v14
	v_mul_f32_e32 v24, 0x4f800000, v14
	s_nop 0
	v_cndmask_b32_e32 v14, v14, v24, vcc
	v_sqrt_f32_e32 v24, v14
	s_nop 0
	v_add_u32_e32 v25, -1, v24
	v_fma_f32 v26, -v25, v24, v14
	v_cmp_ge_f32_e64 s[2:3], 0, v26
	v_add_u32_e32 v26, 1, v24
	s_nop 0
	v_cndmask_b32_e64 v25, v24, v25, s[2:3]
	v_fma_f32 v24, -v26, v24, v14
	v_cmp_lt_f32_e64 s[2:3], 0, v24
	s_nop 1
	v_cndmask_b32_e64 v24, v25, v26, s[2:3]
	v_mul_f32_e32 v25, 0x37800000, v24
	v_cndmask_b32_e32 v24, v24, v25, vcc
	v_cmp_class_f32_e32 vcc, v14, v174
	s_nop 1
	v_cndmask_b32_e32 v14, v24, v14, vcc
	v_mul_f32_e32 v14, v23, v14
	v_rcp_f32_e32 v23, v11
	v_rcp_f32_e64 v11, -v15
	v_mul_f32_e32 v14, v14, v28
	v_mul_f32_e32 v11, v172, v11
	v_add_f32_e32 v15, v11, v11
	v_exp_f32_e32 v15, v15
	s_nop 0
	v_sub_f32_e32 v15, 1.0, v15
	v_max_f32_e32 v15, 0, v15
	v_cmp_gt_f32_e32 vcc, s17, v15
	v_mul_f32_e32 v24, 0x4f800000, v15
	s_nop 0
	v_cndmask_b32_e32 v15, v15, v24, vcc
	v_sqrt_f32_e32 v24, v15
	s_nop 0
	v_add_u32_e32 v25, -1, v24
	v_fma_f32 v26, -v25, v24, v15
	v_cmp_ge_f32_e64 s[2:3], 0, v26
	v_add_u32_e32 v26, 1, v24
	s_nop 0
	v_cndmask_b32_e64 v25, v24, v25, s[2:3]
	v_fma_f32 v24, -v26, v24, v15
	v_cmp_lt_f32_e64 s[2:3], 0, v24
	s_nop 1
	v_cndmask_b32_e64 v24, v25, v26, s[2:3]
	v_mul_f32_e32 v25, 0x37800000, v24
	v_cndmask_b32_e32 v24, v24, v25, vcc
	v_cmp_class_f32_e32 vcc, v15, v174
	s_nop 1
	v_cndmask_b32_e32 v15, v24, v15, vcc
	v_mul_f32_e32 v15, v23, v15
	v_mul_f32_e32 v15, v15, v22
; __device__ __forceinline__ unsigned cvt_pk_bf16(float lo, float hi) { unsigned r; asm volatile("v_cvt_pk_bf16_f32 %0, %1, %2" : "=v"(r) : "v"(lo), "v"(hi)); return r; }
; __device__ __forceinline__ float sigmoidf_(float x) { return __builtin_amdgcn_rcpf(1.0f + __builtin_amdgcn_exp2f(-x * LOG2E)); }
; #define PG8_BAR __builtin_amdgcn_s_barrier()
; #define PG8_RS_FINISH() do { if constexpr (Epi::ROWSCALE) { _Pragma("unroll") for (int ai_ = 0; ai_ < 2; ++ai_) _Pragma("unroll") for (int m_ = 0; m_ < 4; ++m_) rs[ai_][m_] = rsqrtf(fq_sum(rsp[ai_][m_]) * (1.f / DM) + EPS); } \
;         else { _Pragma("unroll") for (int ai_ = 0; ai_ < 2; ++ai_) _Pragma("unroll") for (int m_ = 0; m_ < 4; ++m_) rs[ai_][m_] = 1.f; } } while (0)
; template <class Epi, bool ALIGN_EPI>
; __device__ __forceinline__ void gemm_phase(LAS unsigned char* lds, const Gemm g, const StaticOrder S, const Epi E) {
;     ...
;         if (!has_next) break;
;         PG8_RS_FINISH();
; #pragma unroll
;         for (int a = 0; a < 2; ++a)
; #pragma unroll
;             for (int b = 0; b < 2; ++b)
; #pragma unroll
;                 for (int m = 0; m < 4; ++m)
; #pragma unroll
;                     for (int n = 0; n < 2; ++n) acc[a][b][m][n] = (f32x4){0.f, 0.f, 0.f, 0.f};
;         cur = nxt; cA = nA; cB = nB; ++ui;
;         if constexpr (ALIGN_EPI) { if (wr == 1) PG8_BAR; }
;     __device__ __forceinline__ void operator()(const f32x4 (&acc)[2][2][4][2], const Unit& u, int wr, int wc, int fr, int fq, const float (&rs)[2][4]) const {
;     ...
;                 for (int j = 0; j < 8; ++j) { const float r = sigmoidf_(acc[ai][0][m][j >> 2][j & 3] + ba[j]), ig = sigmoidf_(acc[ai][1][m][j >> 2][j & 3] + bx[j]);
;                     la[j] = -r * sp[j]; const float a2 = __builtin_amdgcn_exp2f(2.0f * la[j]); uu[j] = __builtin_sqrtf(fmaxf(1.0f - a2, 0.0f)) * ig * xc[j]; }
;                 u32x4 w; w.x = cvt_pk_bf16(la[0], la[1]); w.y = cvt_pk_bf16(la[2], la[3]); w.z = cvt_pk_bf16(la[4], la[5]); w.w = cvt_pk_bf16(la[6], la[7]);
;                 *(u32x4*)(LA + (size_t)row * 1024 + dir * 512 + cbase) = w;
;                 w.x = cvt_pk_bf16(uu[0], uu[1]); w.y = cvt_pk_bf16(uu[2], uu[3]); w.z = cvt_pk_bf16(uu[4], uu[5]); w.w = cvt_pk_bf16(uu[6], uu[7]);
;                 *(u32x4*)(U + (size_t)row * 1024 + dir * 512 + cbase) = w; }
	v_add_f32_e32 v22, v4, v4
	v_exp_f32_e32 v22, v22
	s_nop 0
	v_sub_f32_e32 v22, 1.0, v22
	v_max_f32_e32 v22, 0, v22
	v_cmp_gt_f32_e32 vcc, s17, v22
	v_mul_f32_e32 v23, 0x4f800000, v22
	s_nop 0
	v_cndmask_b32_e32 v22, v22, v23, vcc
	v_sqrt_f32_e32 v23, v22
	s_nop 0
	v_add_u32_e32 v24, -1, v23
	v_fma_f32 v25, -v24, v23, v22
	v_cmp_ge_f32_e64 s[2:3], 0, v25
	v_add_u32_e32 v25, 1, v23
	s_nop 0
	v_cndmask_b32_e64 v24, v23, v24, s[2:3]
	v_fma_f32 v23, -v25, v23, v22
	v_cmp_lt_f32_e64 s[2:3], 0, v23
	s_nop 1
	v_cndmask_b32_e64 v23, v24, v25, s[2:3]
	v_mul_f32_e32 v24, 0x37800000, v23
	v_cndmask_b32_e32 v23, v23, v24, vcc
	v_cmp_class_f32_e32 vcc, v22, v174
	s_nop 1
	v_cndmask_b32_e32 v22, v23, v22, vcc
	v_mul_f32_e32 v0, v0, v22
	v_mul_f32_e32 v21, v0, v21
	v_add_f32_e32 v0, v5, v157
	v_mul_f32_e32 v0, 0xbfb8aa3b, v0
	v_exp_f32_e32 v0, v0
	s_nop 0
	v_add_f32_e32 v0, 1.0, v0
	v_rcp_f32_e64 v0, -v0
	s_nop 0
	v_mul_f32_e32 v5, v160, v0
	v_add_f32_e32 v0, v5, v5
	v_exp_f32_e32 v0, v0
	s_nop 0
	v_sub_f32_e32 v0, 1.0, v0
	v_max_f32_e32 v0, 0, v0
	v_cmp_gt_f32_e32 vcc, s17, v0
	v_mul_f32_e32 v22, 0x4f800000, v0
	s_nop 0
	v_cndmask_b32_e32 v0, v0, v22, vcc
	v_sqrt_f32_e32 v22, v0
	s_nop 0
	v_add_u32_e32 v23, -1, v22
	v_fma_f32 v24, -v23, v22, v0
	v_cmp_ge_f32_e64 s[2:3], 0, v24
	v_add_u32_e32 v24, 1, v22
	s_nop 0
	v_cndmask_b32_e64 v23, v22, v23, s[2:3]
	v_fma_f32 v22, -v24, v22, v0
	v_cmp_lt_f32_e64 s[2:3], 0, v22
	s_nop 1
	v_cndmask_b32_e64 v22, v23, v24, s[2:3]
	v_mul_f32_e32 v23, 0x37800000, v22
	v_cndmask_b32_e32 v22, v22, v23, vcc
	v_cmp_class_f32_e32 vcc, v0, v174
	s_nop 1
	v_cndmask_b32_e32 v0, v22, v0, vcc
	v_mul_f32_e32 v0, v1, v0
	v_mul_f32_e32 v20, v0, v20
	v_add_f32_e32 v0, v6, v155
	v_mul_f32_e32 v0, 0xbfb8aa3b, v0
	v_exp_f32_e32 v0, v0
	v_add_f32_e32 v1, v2, v154
	v_mul_f32_e32 v1, 0xbfb8aa3b, v1
	v_exp_f32_e32 v1, v1
	v_add_f32_e32 v0, 1.0, v0
	v_rcp_f32_e64 v0, -v0
	v_add_f32_e32 v1, 1.0, v1
	v_rcp_f32_e32 v1, v1
	v_mul_f32_e32 v6, v149, v0
	v_add_f32_e32 v0, v6, v6
	v_exp_f32_e32 v0, v0
	s_nop 0
	v_sub_f32_e32 v0, 1.0, v0
	v_max_f32_e32 v0, 0, v0
	v_cmp_gt_f32_e32 vcc, s17, v0
	v_mul_f32_e32 v2, 0x4f800000, v0
	s_nop 0
	v_cndmask_b32_e32 v0, v0, v2, vcc
	v_sqrt_f32_e32 v2, v0
	s_nop 0
	v_add_u32_e32 v22, -1, v2
	v_fma_f32 v23, -v22, v2, v0
	v_cmp_ge_f32_e64 s[2:3], 0, v23
	v_add_u32_e32 v23, 1, v2
	s_nop 0
	v_cndmask_b32_e64 v22, v2, v22, s[2:3]
	v_fma_f32 v2, -v23, v2, v0
	v_cmp_lt_f32_e64 s[2:3], 0, v2
	s_nop 1
	v_cndmask_b32_e64 v2, v22, v23, s[2:3]
	v_mul_f32_e32 v22, 0x37800000, v2
	v_cndmask_b32_e32 v2, v2, v22, vcc
	v_cmp_class_f32_e32 vcc, v0, v174
	s_nop 1
	v_cndmask_b32_e32 v0, v2, v0, vcc
	v_mul_f32_e32 v0, v1, v0
	v_mul_f32_e32 v19, v0, v19
	v_add_f32_e32 v0, v7, v147
	v_mul_f32_e32 v0, 0xbfb8aa3b, v0
	v_exp_f32_e32 v0, v0
	v_add_f32_e32 v1, v3, v146
	v_mul_f32_e32 v1, 0xbfb8aa3b, v1
	v_exp_f32_e32 v1, v1
	v_add_f32_e32 v0, 1.0, v0
	v_rcp_f32_e64 v0, -v0
	v_add_f32_e32 v1, 1.0, v1
	v_rcp_f32_e32 v1, v1
	v_mul_f32_e32 v3, v148, v0
	v_add_f32_e32 v0, v3, v3
	v_exp_f32_e32 v0, v0
	s_nop 0
	v_sub_f32_e32 v0, 1.0, v0
	v_max_f32_e32 v0, 0, v0
	v_cmp_gt_f32_e32 vcc, s17, v0
	v_mul_f32_e32 v2, 0x4f800000, v0
	s_nop 0
	v_cndmask_b32_e32 v0, v0, v2, vcc
	v_sqrt_f32_e32 v2, v0
	s_nop 0
	v_add_u32_e32 v7, -1, v2
	v_fma_f32 v22, -v7, v2, v0
	v_cmp_ge_f32_e64 s[2:3], 0, v22
	v_add_u32_e32 v22, 1, v2
	s_nop 0
	v_cndmask_b32_e64 v7, v2, v7, s[2:3]
	v_fma_f32 v2, -v22, v2, v0
	v_cmp_lt_f32_e64 s[2:3], 0, v2
	s_nop 1
	v_cndmask_b32_e64 v2, v7, v22, s[2:3]
	v_mul_f32_e32 v7, 0x37800000, v2
	v_cndmask_b32_e32 v2, v2, v7, vcc
	v_cmp_class_f32_e32 vcc, v0, v174
	s_mov_b64 s[2:3], -1
	s_nop 0
	v_cndmask_b32_e32 v0, v2, v0, vcc
	v_mul_f32_e32 v0, v1, v0
	v_mul_f32_e32 v18, v0, v18
	v_cvt_pk_bf16_f32 v0, v8, v9
	v_cvt_pk_bf16_f32 v1, v10, v11
	v_cvt_pk_bf16_f32 v2, v4, v5
	v_lshlrev_b64 v[4:5], 11, v[16:17]
	v_cvt_pk_bf16_f32 v3, v6, v3
	v_lshl_add_u64 v[6:7], s[76:77], 0, v[4:5]
	v_lshl_add_u64 v[4:5], s[56:57], 0, v[4:5]
	v_lshl_add_u64 v[6:7], v[6:7], 0, s[64:65]
	v_lshl_add_u64 v[4:5], v[4:5], 0, s[64:65]
	v_lshl_add_u64 v[6:7], v[6:7], 0, v[142:143]
	v_lshl_add_u64 v[4:5], v[4:5], 0, v[142:143]
	s_andn2_b64 vcc, exec, s[42:43]
	global_store_dwordx4 v[6:7], v[0:3], off
	s_nop 1
	v_cvt_pk_bf16_f32 v0, v12, v13
	v_cvt_pk_bf16_f32 v1, v14, v15
	v_cvt_pk_bf16_f32 v2, v21, v20
	v_cvt_pk_bf16_f32 v3, v19, v18
	global_store_dwordx4 v[4:5], v[0:3], off
	s_cbranch_vccnz .LBB0_1048
	s_andn2_b64 vcc, exec, s[44:45]
	s_cbranch_vccnz .LBB0_1047
	s_barrier
	s_branch .LBB0_1047
